# GEMM K-loops: back-edge rotation (pointer bumps and trip test moved in front of the iteration's last barrier, docs 7.11)
# baseline (speedup 1.0000x reference)
.LBB0_92:
	s_add_i32 s21, s20, 2
	s_add_u32 s12, s28, 0x80
	s_addc_u32 s13, s29, 0
	s_add_i32 s36, 0, 0x10000
	s_cmp_eq_u32 s1, s20
	s_cselect_b32 s59, s5, s13
	s_cselect_b32 s58, s4, s12
	s_cselect_b32 s13, s57, s19
	s_cselect_b32 s12, s56, s18
	s_add_i32 s20, 0, 0x14000
	v_add_u32_e32 v60, s36, v175
	v_add_u32_e32 v76, s20, v175
	ds_read_b128 v[48:51], v60
	ds_read_b128 v[52:55], v60 offset:1024
	ds_read_b128 v[56:59], v60 offset:2048
	ds_read_b128 v[60:63], v60 offset:3072
	ds_read_b128 v[64:67], v76
	ds_read_b128 v[68:71], v76 offset:1024
	ds_read_b128 v[72:75], v76 offset:2048
	ds_read_b128 v[76:79], v76 offset:3072
	s_add_i32 m0, s72, 0xc000
	ds_read_b128 v[170:173], v177
	ds_read_b128 v[178:181], v177 offset:1024
	ds_read_b128 v[182:185], v177 offset:2048
	ds_read_b128 v[186:189], v177 offset:3072
	ds_read_b128 v[194:197], v177 offset:4096
	ds_read_b128 v[198:201], v177 offset:5120
	ds_read_b128 v[202:205], v177 offset:6144
	ds_read_b128 v[212:215], v177 offset:7168
	global_load_lds_dwordx4 v166, s[28:29]
	s_add_i32 m0, s72, 0xe000
	s_nop 0
	global_load_lds_dwordx4 v168, s[28:29]
	s_waitcnt vmcnt(8)
	s_waitcnt lgkmcnt(0)
	s_barrier
	s_setprio 1
	v_mfma_f32_16x16x32_bf16 v[156:159], v[48:51], v[170:173], v[156:159]
	v_mfma_f32_16x16x32_bf16 v[152:155], v[56:59], v[170:173], v[152:155]
	v_mfma_f32_16x16x32_bf16 v[140:143], v[48:51], v[182:185], v[140:143]
	v_mfma_f32_16x16x32_bf16 v[136:139], v[56:59], v[182:185], v[136:139]
	v_mfma_f32_16x16x32_bf16 v[124:127], v[48:51], v[194:197], v[124:127]
	v_mfma_f32_16x16x32_bf16 v[120:123], v[56:59], v[194:197], v[120:123]
	v_mfma_f32_16x16x32_bf16 v[108:111], v[48:51], v[202:205], v[108:111]
	v_mfma_f32_16x16x32_bf16 v[104:107], v[56:59], v[202:205], v[104:107]
	v_mfma_f32_16x16x32_bf16 v[156:159], v[52:55], v[178:181], v[156:159]
	v_mfma_f32_16x16x32_bf16 v[152:155], v[60:63], v[178:181], v[152:155]
	v_mfma_f32_16x16x32_bf16 v[140:143], v[52:55], v[186:189], v[140:143]
	v_mfma_f32_16x16x32_bf16 v[136:139], v[60:63], v[186:189], v[136:139]
	v_mfma_f32_16x16x32_bf16 v[124:127], v[52:55], v[198:201], v[124:127]
	v_mfma_f32_16x16x32_bf16 v[120:123], v[60:63], v[198:201], v[120:123]
	v_mfma_f32_16x16x32_bf16 v[108:111], v[52:55], v[212:215], v[108:111]
	v_mfma_f32_16x16x32_bf16 v[104:107], v[60:63], v[212:215], v[104:107]
	v_mfma_f32_16x16x32_bf16 v[148:151], v[64:67], v[170:173], v[148:151]
	v_mfma_f32_16x16x32_bf16 v[144:147], v[72:75], v[170:173], v[144:147]
	v_mfma_f32_16x16x32_bf16 v[132:135], v[64:67], v[182:185], v[132:135]
	v_mfma_f32_16x16x32_bf16 v[128:131], v[72:75], v[182:185], v[128:131]
	v_mfma_f32_16x16x32_bf16 v[116:119], v[64:67], v[194:197], v[116:119]
	v_mfma_f32_16x16x32_bf16 v[112:115], v[72:75], v[194:197], v[112:115]
	v_mfma_f32_16x16x32_bf16 v[100:103], v[64:67], v[202:205], v[100:103]
	v_mfma_f32_16x16x32_bf16 v[96:99], v[72:75], v[202:205], v[96:99]
	v_mfma_f32_16x16x32_bf16 v[148:151], v[68:71], v[178:181], v[148:151]
	v_mfma_f32_16x16x32_bf16 v[144:147], v[76:79], v[178:181], v[144:147]
	v_mfma_f32_16x16x32_bf16 v[132:135], v[68:71], v[186:189], v[132:135]
	v_mfma_f32_16x16x32_bf16 v[128:131], v[76:79], v[186:189], v[128:131]
	v_mfma_f32_16x16x32_bf16 v[116:119], v[68:71], v[198:201], v[116:119]
	v_mfma_f32_16x16x32_bf16 v[112:115], v[76:79], v[198:201], v[112:115]
	v_mfma_f32_16x16x32_bf16 v[100:103], v[68:71], v[212:215], v[100:103]
	v_mfma_f32_16x16x32_bf16 v[96:99], v[76:79], v[212:215], v[96:99]
	s_setprio 0
	s_barrier
	s_add_i32 s36, s36, s9
	s_mov_b64 vcc, s[12:13]
	s_mov_b32 m0, s36
	ds_read_b128 v[170:173], v177 offset:16384
	ds_read_b128 v[178:181], v177 offset:17408
	ds_read_b128 v[182:185], v177 offset:18432
	ds_read_b128 v[186:189], v177 offset:19456
	ds_read_b128 v[194:197], v177 offset:20480
	ds_read_b128 v[198:201], v177 offset:21504
	ds_read_b128 v[202:205], v177 offset:22528
	ds_read_b128 v[212:215], v177 offset:23552
	global_load_lds_dwordx4 v192, s[12:13]
	s_add_i32 m0, s36, 0x2000
	s_add_i32 s20, s20, s9
	global_load_lds_dwordx4 v160, s[12:13]
	s_add_u32 s12, s12, s10
	s_addc_u32 s13, s13, 0
	s_mov_b32 m0, s20
	s_nop 0
	global_load_lds_dwordx4 v192, s[12:13]
	s_add_i32 m0, s20, 0x2000
	s_nop 0
	global_load_lds_dwordx4 v160, s[12:13]
	s_mov_b32 m0, s72
	s_nop 0
	global_load_lds_dwordx4 v164, s[58:59]
	s_mov_b32 m0, s73
	s_nop 0
	global_load_lds_dwordx4 v162, s[58:59]
	s_waitcnt vmcnt(8)
	s_waitcnt lgkmcnt(0)
	s_barrier
	s_setprio 1
	v_mfma_f32_16x16x32_bf16 v[92:95], v[48:51], v[170:173], v[92:95]
	v_mfma_f32_16x16x32_bf16 v[88:91], v[56:59], v[170:173], v[88:91]
	v_mfma_f32_16x16x32_bf16 v[44:47], v[48:51], v[182:185], v[44:47]
	v_mfma_f32_16x16x32_bf16 v[40:43], v[56:59], v[182:185], v[40:43]
	v_mfma_f32_16x16x32_bf16 v[28:31], v[48:51], v[194:197], v[28:31]
	v_mfma_f32_16x16x32_bf16 v[24:27], v[56:59], v[194:197], v[24:27]
	v_mfma_f32_16x16x32_bf16 v[12:15], v[48:51], v[202:205], v[12:15]
	v_mfma_f32_16x16x32_bf16 v[8:11], v[56:59], v[202:205], v[8:11]
	v_mfma_f32_16x16x32_bf16 v[92:95], v[52:55], v[178:181], v[92:95]
	v_mfma_f32_16x16x32_bf16 v[88:91], v[60:63], v[178:181], v[88:91]
	v_mfma_f32_16x16x32_bf16 v[44:47], v[52:55], v[186:189], v[44:47]
	v_mfma_f32_16x16x32_bf16 v[40:43], v[60:63], v[186:189], v[40:43]
	v_mfma_f32_16x16x32_bf16 v[28:31], v[52:55], v[198:201], v[28:31]
	v_mfma_f32_16x16x32_bf16 v[24:27], v[60:63], v[198:201], v[24:27]
	v_mfma_f32_16x16x32_bf16 v[12:15], v[52:55], v[212:215], v[12:15]
	v_mfma_f32_16x16x32_bf16 v[8:11], v[60:63], v[212:215], v[8:11]
	v_mfma_f32_16x16x32_bf16 v[36:39], v[64:67], v[182:185], v[36:39]
	v_mfma_f32_16x16x32_bf16 v[32:35], v[72:75], v[182:185], v[32:35]
	v_mfma_f32_16x16x32_bf16 v[20:23], v[64:67], v[194:197], v[20:23]
	v_mfma_f32_16x16x32_bf16 v[16:19], v[72:75], v[194:197], v[16:19]
	v_mfma_f32_16x16x32_bf16 v[4:7], v[64:67], v[202:205], v[4:7]
	v_mfma_f32_16x16x32_bf16 v[0:3], v[72:75], v[202:205], v[0:3]
	v_mfma_f32_16x16x32_bf16 v[48:51], v[64:67], v[170:173], v[84:87]
	v_mfma_f32_16x16x32_bf16 v[52:55], v[72:75], v[170:173], v[80:83]
	v_mfma_f32_16x16x32_bf16 v[36:39], v[68:71], v[186:189], v[36:39]
	v_mfma_f32_16x16x32_bf16 v[32:35], v[76:79], v[186:189], v[32:35]
	v_mfma_f32_16x16x32_bf16 v[20:23], v[68:71], v[198:201], v[20:23]
	v_mfma_f32_16x16x32_bf16 v[16:19], v[76:79], v[198:201], v[16:19]
	v_mfma_f32_16x16x32_bf16 v[4:7], v[68:71], v[212:215], v[4:7]
	v_mfma_f32_16x16x32_bf16 v[0:3], v[76:79], v[212:215], v[0:3]
	v_mfma_f32_16x16x32_bf16 v[48:51], v[68:71], v[178:181], v[48:51]
	v_mfma_f32_16x16x32_bf16 v[52:55], v[76:79], v[178:181], v[52:55]
	s_setprio 0
	s_barrier
	s_add_i32 s20, 0, 0x18000
	s_add_i32 s36, 0, 0x1c000
	v_add_u32_e32 v68, s20, v175
	v_add_u32_e32 v80, s36, v175
	ds_read_b128 v[56:59], v68
	ds_read_b128 v[60:63], v68 offset:1024
	ds_read_b128 v[64:67], v68 offset:2048
	ds_read_b128 v[68:71], v68 offset:3072
	ds_read_b128 v[72:75], v80
	ds_read_b128 v[76:79], v80 offset:1024
	ds_read_b128 v[170:173], v80 offset:2048
	ds_read_b128 v[178:181], v80 offset:3072
	s_add_u32 s12, s58, s30
	s_addc_u32 s13, s59, 0
	s_mov_b32 m0, s74
	ds_read_b128 v[80:83], v177 offset:32768
	ds_read_b128 v[84:87], v177 offset:33792
	ds_read_b128 v[182:185], v177 offset:34816
	ds_read_b128 v[186:189], v177 offset:35840
	ds_read_b128 v[194:197], v177 offset:36864
	ds_read_b128 v[198:201], v177 offset:37888
	ds_read_b128 v[202:205], v177 offset:38912
	ds_read_b128 v[212:215], v177 offset:39936
	global_load_lds_dwordx4 v164, s[12:13]
	s_mov_b32 m0, s75
	s_nop 0
	global_load_lds_dwordx4 v162, s[12:13]
	s_waitcnt vmcnt(8)
	s_waitcnt lgkmcnt(0)
	s_barrier
	s_setprio 1
	v_mfma_f32_16x16x32_bf16 v[156:159], v[56:59], v[80:83], v[156:159]
	v_mfma_f32_16x16x32_bf16 v[152:155], v[64:67], v[80:83], v[152:155]
	v_mfma_f32_16x16x32_bf16 v[140:143], v[56:59], v[182:185], v[140:143]
	v_mfma_f32_16x16x32_bf16 v[136:139], v[64:67], v[182:185], v[136:139]
	v_mfma_f32_16x16x32_bf16 v[124:127], v[56:59], v[194:197], v[124:127]
	v_mfma_f32_16x16x32_bf16 v[120:123], v[64:67], v[194:197], v[120:123]
	v_mfma_f32_16x16x32_bf16 v[108:111], v[56:59], v[202:205], v[108:111]
	v_mfma_f32_16x16x32_bf16 v[104:107], v[64:67], v[202:205], v[104:107]
	v_mfma_f32_16x16x32_bf16 v[156:159], v[60:63], v[84:87], v[156:159]
	v_mfma_f32_16x16x32_bf16 v[152:155], v[68:71], v[84:87], v[152:155]
	v_mfma_f32_16x16x32_bf16 v[140:143], v[60:63], v[186:189], v[140:143]
	v_mfma_f32_16x16x32_bf16 v[136:139], v[68:71], v[186:189], v[136:139]
	v_mfma_f32_16x16x32_bf16 v[124:127], v[60:63], v[198:201], v[124:127]
	v_mfma_f32_16x16x32_bf16 v[120:123], v[68:71], v[198:201], v[120:123]
	v_mfma_f32_16x16x32_bf16 v[108:111], v[60:63], v[212:215], v[108:111]
	v_mfma_f32_16x16x32_bf16 v[104:107], v[68:71], v[212:215], v[104:107]
	v_mfma_f32_16x16x32_bf16 v[148:151], v[72:75], v[80:83], v[148:151]
	v_mfma_f32_16x16x32_bf16 v[80:83], v[170:173], v[80:83], v[144:147]
	v_mfma_f32_16x16x32_bf16 v[144:147], v[178:181], v[84:87], v[80:83]
	v_mfma_f32_16x16x32_bf16 v[80:83], v[72:75], v[182:185], v[132:135]
	v_mfma_f32_16x16x32_bf16 v[132:135], v[76:79], v[186:189], v[80:83]
	v_mfma_f32_16x16x32_bf16 v[80:83], v[170:173], v[182:185], v[128:131]
	v_mfma_f32_16x16x32_bf16 v[128:131], v[178:181], v[186:189], v[80:83]
	v_mfma_f32_16x16x32_bf16 v[80:83], v[72:75], v[194:197], v[116:119]
	v_mfma_f32_16x16x32_bf16 v[116:119], v[76:79], v[198:201], v[80:83]
	v_mfma_f32_16x16x32_bf16 v[80:83], v[170:173], v[194:197], v[112:115]
	v_mfma_f32_16x16x32_bf16 v[112:115], v[178:181], v[198:201], v[80:83]
	v_mfma_f32_16x16x32_bf16 v[80:83], v[72:75], v[202:205], v[100:103]
	v_mfma_f32_16x16x32_bf16 v[100:103], v[76:79], v[212:215], v[80:83]
	v_mfma_f32_16x16x32_bf16 v[80:83], v[170:173], v[202:205], v[96:99]
	v_mfma_f32_16x16x32_bf16 v[148:151], v[76:79], v[84:87], v[148:151]
	v_mfma_f32_16x16x32_bf16 v[96:99], v[178:181], v[212:215], v[80:83]
	s_setprio 0
	s_barrier
	s_add_i32 m0, s20, s9
	s_add_u32 s12, vcc_lo, 0x80
	s_addc_u32 s13, vcc_hi, 0
	ds_read_b128 v[80:83], v177 offset:49152
	ds_read_b128 v[182:185], v177 offset:50176
	ds_read_b128 v[186:189], v177 offset:51200
	ds_read_b128 v[194:197], v177 offset:52224
	ds_read_b128 v[198:201], v177 offset:53248
	ds_read_b128 v[202:205], v177 offset:54272
	ds_read_b128 v[212:215], v177 offset:55296
	ds_read_b128 v[242:245], v177 offset:56320
	global_load_lds_dwordx4 v192, s[12:13]
	s_add_i32 m0, m0, 0x2000
	s_nop 0
	global_load_lds_dwordx4 v160, s[12:13]
	s_add_u32 s12, s12, s10
	s_addc_u32 s13, s13, 0
	s_add_i32 m0, s36, s9
	s_nop 0
	global_load_lds_dwordx4 v192, s[12:13]
	s_add_i32 m0, m0, 0x2000
	s_nop 0
	global_load_lds_dwordx4 v160, s[12:13]
	s_add_u32 s12, s58, 0x80
	s_addc_u32 s13, s59, 0
	s_mov_b32 m0, s76
	s_nop 0
	global_load_lds_dwordx4 v164, s[12:13]
	s_mov_b32 m0, s77
	s_nop 0
	global_load_lds_dwordx4 v162, s[12:13]
	s_waitcnt vmcnt(8)
	s_waitcnt lgkmcnt(0)
	s_barrier
	s_setprio 1
	v_mfma_f32_16x16x32_bf16 v[84:87], v[56:59], v[80:83], v[92:95]
	v_mfma_f32_16x16x32_bf16 v[92:95], v[60:63], v[182:185], v[84:87]
	v_mfma_f32_16x16x32_bf16 v[84:87], v[64:67], v[80:83], v[88:91]
	v_mfma_f32_16x16x32_bf16 v[44:47], v[56:59], v[186:189], v[44:47]
	v_mfma_f32_16x16x32_bf16 v[40:43], v[64:67], v[186:189], v[40:43]
	v_mfma_f32_16x16x32_bf16 v[28:31], v[56:59], v[198:201], v[28:31]
	v_mfma_f32_16x16x32_bf16 v[24:27], v[64:67], v[198:201], v[24:27]
	v_mfma_f32_16x16x32_bf16 v[12:15], v[56:59], v[212:215], v[12:15]
	v_mfma_f32_16x16x32_bf16 v[8:11], v[64:67], v[212:215], v[8:11]
	v_mfma_f32_16x16x32_bf16 v[88:91], v[68:71], v[182:185], v[84:87]
	v_mfma_f32_16x16x32_bf16 v[44:47], v[60:63], v[194:197], v[44:47]
	v_mfma_f32_16x16x32_bf16 v[40:43], v[68:71], v[194:197], v[40:43]
	v_mfma_f32_16x16x32_bf16 v[28:31], v[60:63], v[202:205], v[28:31]
	v_mfma_f32_16x16x32_bf16 v[24:27], v[68:71], v[202:205], v[24:27]
	v_mfma_f32_16x16x32_bf16 v[12:15], v[60:63], v[242:245], v[12:15]
	v_mfma_f32_16x16x32_bf16 v[8:11], v[68:71], v[242:245], v[8:11]
	v_mfma_f32_16x16x32_bf16 v[48:51], v[72:75], v[80:83], v[48:51]
	v_mfma_f32_16x16x32_bf16 v[84:87], v[76:79], v[182:185], v[48:51]
	v_mfma_f32_16x16x32_bf16 v[48:51], v[170:173], v[80:83], v[52:55]
	v_mfma_f32_16x16x32_bf16 v[36:39], v[72:75], v[186:189], v[36:39]
	v_mfma_f32_16x16x32_bf16 v[32:35], v[170:173], v[186:189], v[32:35]
	v_mfma_f32_16x16x32_bf16 v[20:23], v[72:75], v[198:201], v[20:23]
	v_mfma_f32_16x16x32_bf16 v[16:19], v[170:173], v[198:201], v[16:19]
	v_mfma_f32_16x16x32_bf16 v[4:7], v[72:75], v[212:215], v[4:7]
	v_mfma_f32_16x16x32_bf16 v[0:3], v[170:173], v[212:215], v[0:3]
	v_mfma_f32_16x16x32_bf16 v[80:83], v[178:181], v[182:185], v[48:51]
	v_mfma_f32_16x16x32_bf16 v[36:39], v[76:79], v[194:197], v[36:39]
	v_mfma_f32_16x16x32_bf16 v[32:35], v[178:181], v[194:197], v[32:35]
	v_mfma_f32_16x16x32_bf16 v[20:23], v[76:79], v[202:205], v[20:23]
	v_mfma_f32_16x16x32_bf16 v[16:19], v[178:181], v[202:205], v[16:19]
	v_mfma_f32_16x16x32_bf16 v[4:7], v[76:79], v[242:245], v[4:7]
	v_mfma_f32_16x16x32_bf16 v[0:3], v[178:181], v[242:245], v[0:3]
	s_setprio 0
	s_add_u32 s28, s28, 0x100
	s_addc_u32 s29, s29, 0
	s_add_u32 s18, s18, 0x100
	s_addc_u32 s19, s19, 0
	s_cmp_ge_u32 s21, s11
	s_mov_b32 s20, s21
	s_barrier
	s_cbranch_scc0 .LBB0_92

.LBB0_113:
	s_add_i32 s21, s20, 2
	s_add_u32 s12, s28, 0x80
	s_addc_u32 s13, s29, 0
	s_add_i32 s36, 0, 0x10000
	s_cmp_eq_u32 s85, s20
	s_cselect_b32 s59, s5, s13
	s_cselect_b32 s58, s4, s12
	v_add_u32_e32 v142, s36, v145
	s_cselect_b32 s13, s57, s19
	s_cselect_b32 s12, s56, s18
	s_add_i32 s20, 0, 0x14000
	ds_read_b128 v[138:141], v142
	ds_read_b128 v[148:151], v142 offset:1024
	ds_read_b128 v[152:155], v142 offset:2048
	ds_read_b128 v[156:159], v142 offset:3072
	v_add_u32_e32 v142, s20, v145
	ds_read_b128 v[160:163], v142
	ds_read_b128 v[164:167], v142 offset:1024
	ds_read_b128 v[168:171], v142 offset:2048
	ds_read_b128 v[172:175], v142 offset:3072
	s_add_i32 m0, s77, 0xc000
	ds_read_b128 v[176:179], v147
	ds_read_b128 v[180:183], v147 offset:1024
	ds_read_b128 v[184:187], v147 offset:2048
	ds_read_b128 v[188:191], v147 offset:3072
	ds_read_b128 v[194:197], v147 offset:4096
	ds_read_b128 v[198:201], v147 offset:5120
	ds_read_b128 v[202:205], v147 offset:6144
	ds_read_b128 v[212:215], v147 offset:7168
	global_load_lds_dwordx4 v134, s[28:29]
	s_add_i32 m0, s77, 0xe000
	s_nop 0
	global_load_lds_dwordx4 v136, s[28:29]
	s_waitcnt vmcnt(8)
	s_waitcnt lgkmcnt(0)
	s_barrier
	s_setprio 1
	v_mfma_f32_16x16x32_bf16 v[124:127], v[138:141], v[176:179], v[124:127]
	v_mfma_f32_16x16x32_bf16 v[120:123], v[152:155], v[176:179], v[120:123]
	v_mfma_f32_16x16x32_bf16 v[108:111], v[138:141], v[184:187], v[108:111]
	v_mfma_f32_16x16x32_bf16 v[104:107], v[152:155], v[184:187], v[104:107]
	v_mfma_f32_16x16x32_bf16 v[92:95], v[138:141], v[194:197], v[92:95]
	v_mfma_f32_16x16x32_bf16 v[88:91], v[152:155], v[194:197], v[88:91]
	v_mfma_f32_16x16x32_bf16 v[76:79], v[138:141], v[202:205], v[76:79]
	v_mfma_f32_16x16x32_bf16 v[72:75], v[152:155], v[202:205], v[72:75]
	v_mfma_f32_16x16x32_bf16 v[124:127], v[148:151], v[180:183], v[124:127]
	v_mfma_f32_16x16x32_bf16 v[120:123], v[156:159], v[180:183], v[120:123]
	v_mfma_f32_16x16x32_bf16 v[108:111], v[148:151], v[188:191], v[108:111]
	v_mfma_f32_16x16x32_bf16 v[104:107], v[156:159], v[188:191], v[104:107]
	v_mfma_f32_16x16x32_bf16 v[92:95], v[148:151], v[198:201], v[92:95]
	v_mfma_f32_16x16x32_bf16 v[88:91], v[156:159], v[198:201], v[88:91]
	v_mfma_f32_16x16x32_bf16 v[76:79], v[148:151], v[212:215], v[76:79]
	v_mfma_f32_16x16x32_bf16 v[72:75], v[156:159], v[212:215], v[72:75]
	v_mfma_f32_16x16x32_bf16 v[116:119], v[160:163], v[176:179], v[116:119]
	v_mfma_f32_16x16x32_bf16 v[112:115], v[168:171], v[176:179], v[112:115]
	v_mfma_f32_16x16x32_bf16 v[100:103], v[160:163], v[184:187], v[100:103]
	v_mfma_f32_16x16x32_bf16 v[96:99], v[168:171], v[184:187], v[96:99]
	v_mfma_f32_16x16x32_bf16 v[84:87], v[160:163], v[194:197], v[84:87]
	v_mfma_f32_16x16x32_bf16 v[80:83], v[168:171], v[194:197], v[80:83]
	v_mfma_f32_16x16x32_bf16 v[68:71], v[160:163], v[202:205], v[68:71]
	v_mfma_f32_16x16x32_bf16 v[64:67], v[168:171], v[202:205], v[64:67]
	v_mfma_f32_16x16x32_bf16 v[116:119], v[164:167], v[180:183], v[116:119]
	v_mfma_f32_16x16x32_bf16 v[112:115], v[172:175], v[180:183], v[112:115]
	v_mfma_f32_16x16x32_bf16 v[100:103], v[164:167], v[188:191], v[100:103]
	v_mfma_f32_16x16x32_bf16 v[96:99], v[172:175], v[188:191], v[96:99]
	v_mfma_f32_16x16x32_bf16 v[84:87], v[164:167], v[198:201], v[84:87]
	v_mfma_f32_16x16x32_bf16 v[80:83], v[172:175], v[198:201], v[80:83]
	v_mfma_f32_16x16x32_bf16 v[68:71], v[164:167], v[212:215], v[68:71]
	v_mfma_f32_16x16x32_bf16 v[64:67], v[172:175], v[212:215], v[64:67]
	s_setprio 0
	s_barrier
	s_add_i32 s36, s36, s71
	s_mov_b64 vcc, s[12:13]
	s_mov_b32 m0, s36
	ds_read_b128 v[176:179], v147 offset:16384
	ds_read_b128 v[180:183], v147 offset:17408
	ds_read_b128 v[184:187], v147 offset:18432
	ds_read_b128 v[188:191], v147 offset:19456
	ds_read_b128 v[194:197], v147 offset:20480
	ds_read_b128 v[198:201], v147 offset:21504
	ds_read_b128 v[202:205], v147 offset:22528
	ds_read_b128 v[212:215], v147 offset:23552
	global_load_lds_dwordx4 v192, s[12:13]
	s_add_i32 m0, s36, 0x2000
	s_add_i32 s20, s20, s71
	global_load_lds_dwordx4 v128, s[12:13]
	s_add_u32 s12, s12, s9
	s_addc_u32 s13, s13, 0
	s_mov_b32 m0, s20
	s_nop 0
	global_load_lds_dwordx4 v192, s[12:13]
	s_add_i32 m0, s20, 0x2000
	s_nop 0
	global_load_lds_dwordx4 v128, s[12:13]
	s_mov_b32 m0, s77
	s_nop 0
	global_load_lds_dwordx4 v132, s[58:59]
	s_mov_b32 m0, s78
	s_nop 0
	global_load_lds_dwordx4 v130, s[58:59]
	s_waitcnt vmcnt(8)
	s_waitcnt lgkmcnt(0)
	s_barrier
	s_setprio 1
	v_mfma_f32_16x16x32_bf16 v[60:63], v[138:141], v[176:179], v[60:63]
	v_mfma_f32_16x16x32_bf16 v[56:59], v[152:155], v[176:179], v[56:59]
	v_mfma_f32_16x16x32_bf16 v[44:47], v[138:141], v[184:187], v[44:47]
	v_mfma_f32_16x16x32_bf16 v[40:43], v[152:155], v[184:187], v[40:43]
	v_mfma_f32_16x16x32_bf16 v[28:31], v[138:141], v[194:197], v[28:31]
	v_mfma_f32_16x16x32_bf16 v[24:27], v[152:155], v[194:197], v[24:27]
	v_mfma_f32_16x16x32_bf16 v[12:15], v[138:141], v[202:205], v[12:15]
	v_mfma_f32_16x16x32_bf16 v[8:11], v[152:155], v[202:205], v[8:11]
	v_mfma_f32_16x16x32_bf16 v[60:63], v[148:151], v[180:183], v[60:63]
	v_mfma_f32_16x16x32_bf16 v[56:59], v[156:159], v[180:183], v[56:59]
	v_mfma_f32_16x16x32_bf16 v[44:47], v[148:151], v[188:191], v[44:47]
	v_mfma_f32_16x16x32_bf16 v[40:43], v[156:159], v[188:191], v[40:43]
	v_mfma_f32_16x16x32_bf16 v[28:31], v[148:151], v[198:201], v[28:31]
	v_mfma_f32_16x16x32_bf16 v[24:27], v[156:159], v[198:201], v[24:27]
	v_mfma_f32_16x16x32_bf16 v[12:15], v[148:151], v[212:215], v[12:15]
	v_mfma_f32_16x16x32_bf16 v[8:11], v[156:159], v[212:215], v[8:11]
	v_mfma_f32_16x16x32_bf16 v[52:55], v[160:163], v[176:179], v[52:55]
	v_mfma_f32_16x16x32_bf16 v[48:51], v[168:171], v[176:179], v[48:51]
	v_mfma_f32_16x16x32_bf16 v[36:39], v[160:163], v[184:187], v[36:39]
	v_mfma_f32_16x16x32_bf16 v[32:35], v[168:171], v[184:187], v[32:35]
	v_mfma_f32_16x16x32_bf16 v[20:23], v[160:163], v[194:197], v[20:23]
	v_mfma_f32_16x16x32_bf16 v[16:19], v[168:171], v[194:197], v[16:19]
	v_mfma_f32_16x16x32_bf16 v[4:7], v[160:163], v[202:205], v[4:7]
	v_mfma_f32_16x16x32_bf16 v[0:3], v[168:171], v[202:205], v[0:3]
	v_mfma_f32_16x16x32_bf16 v[52:55], v[164:167], v[180:183], v[52:55]
	v_mfma_f32_16x16x32_bf16 v[48:51], v[172:175], v[180:183], v[48:51]
	v_mfma_f32_16x16x32_bf16 v[36:39], v[164:167], v[188:191], v[36:39]
	v_mfma_f32_16x16x32_bf16 v[32:35], v[172:175], v[188:191], v[32:35]
	v_mfma_f32_16x16x32_bf16 v[20:23], v[164:167], v[198:201], v[20:23]
	v_mfma_f32_16x16x32_bf16 v[16:19], v[172:175], v[198:201], v[16:19]
	v_mfma_f32_16x16x32_bf16 v[4:7], v[164:167], v[212:215], v[4:7]
	v_mfma_f32_16x16x32_bf16 v[0:3], v[172:175], v[212:215], v[0:3]
	s_setprio 0
	s_barrier
	s_add_i32 s20, 0, 0x18000
	s_add_i32 s36, 0, 0x1c000
	v_add_u32_e32 v156, s20, v145
	v_add_u32_e32 v172, s36, v145
	ds_read_b128 v[138:141], v156
	ds_read_b128 v[148:151], v156 offset:1024
	ds_read_b128 v[152:155], v156 offset:2048
	ds_read_b128 v[156:159], v156 offset:3072
	ds_read_b128 v[160:163], v172
	ds_read_b128 v[164:167], v172 offset:1024
	ds_read_b128 v[168:171], v172 offset:2048
	ds_read_b128 v[172:175], v172 offset:3072
	s_add_u32 s12, s58, s34
	s_addc_u32 s13, s59, 0
	s_mov_b32 m0, s79
	ds_read_b128 v[176:179], v147 offset:32768
	ds_read_b128 v[180:183], v147 offset:33792
	ds_read_b128 v[184:187], v147 offset:34816
	ds_read_b128 v[188:191], v147 offset:35840
	ds_read_b128 v[194:197], v147 offset:36864
	ds_read_b128 v[198:201], v147 offset:37888
	ds_read_b128 v[202:205], v147 offset:38912
	ds_read_b128 v[212:215], v147 offset:39936
	global_load_lds_dwordx4 v132, s[12:13]
	s_mov_b32 m0, s80
	s_nop 0
	global_load_lds_dwordx4 v130, s[12:13]
	s_waitcnt vmcnt(8)
	s_waitcnt lgkmcnt(0)
	s_barrier
	s_setprio 1
	v_mfma_f32_16x16x32_bf16 v[124:127], v[138:141], v[176:179], v[124:127]
	v_mfma_f32_16x16x32_bf16 v[120:123], v[152:155], v[176:179], v[120:123]
	v_mfma_f32_16x16x32_bf16 v[108:111], v[138:141], v[184:187], v[108:111]
	v_mfma_f32_16x16x32_bf16 v[104:107], v[152:155], v[184:187], v[104:107]
	v_mfma_f32_16x16x32_bf16 v[92:95], v[138:141], v[194:197], v[92:95]
	v_mfma_f32_16x16x32_bf16 v[88:91], v[152:155], v[194:197], v[88:91]
	v_mfma_f32_16x16x32_bf16 v[76:79], v[138:141], v[202:205], v[76:79]
	v_mfma_f32_16x16x32_bf16 v[72:75], v[152:155], v[202:205], v[72:75]
	v_mfma_f32_16x16x32_bf16 v[124:127], v[148:151], v[180:183], v[124:127]
	v_mfma_f32_16x16x32_bf16 v[120:123], v[156:159], v[180:183], v[120:123]
	v_mfma_f32_16x16x32_bf16 v[108:111], v[148:151], v[188:191], v[108:111]
	v_mfma_f32_16x16x32_bf16 v[104:107], v[156:159], v[188:191], v[104:107]
	v_mfma_f32_16x16x32_bf16 v[92:95], v[148:151], v[198:201], v[92:95]
	v_mfma_f32_16x16x32_bf16 v[88:91], v[156:159], v[198:201], v[88:91]
	v_mfma_f32_16x16x32_bf16 v[76:79], v[148:151], v[212:215], v[76:79]
	v_mfma_f32_16x16x32_bf16 v[72:75], v[156:159], v[212:215], v[72:75]
	v_mfma_f32_16x16x32_bf16 v[116:119], v[160:163], v[176:179], v[116:119]
	v_mfma_f32_16x16x32_bf16 v[112:115], v[168:171], v[176:179], v[112:115]
	v_mfma_f32_16x16x32_bf16 v[100:103], v[160:163], v[184:187], v[100:103]
	v_mfma_f32_16x16x32_bf16 v[96:99], v[168:171], v[184:187], v[96:99]
	v_mfma_f32_16x16x32_bf16 v[84:87], v[160:163], v[194:197], v[84:87]
	v_mfma_f32_16x16x32_bf16 v[80:83], v[168:171], v[194:197], v[80:83]
	v_mfma_f32_16x16x32_bf16 v[68:71], v[160:163], v[202:205], v[68:71]
	v_mfma_f32_16x16x32_bf16 v[64:67], v[168:171], v[202:205], v[64:67]
	v_mfma_f32_16x16x32_bf16 v[116:119], v[164:167], v[180:183], v[116:119]
	v_mfma_f32_16x16x32_bf16 v[112:115], v[172:175], v[180:183], v[112:115]
	v_mfma_f32_16x16x32_bf16 v[100:103], v[164:167], v[188:191], v[100:103]
	v_mfma_f32_16x16x32_bf16 v[96:99], v[172:175], v[188:191], v[96:99]
	v_mfma_f32_16x16x32_bf16 v[84:87], v[164:167], v[198:201], v[84:87]
	v_mfma_f32_16x16x32_bf16 v[80:83], v[172:175], v[198:201], v[80:83]
	v_mfma_f32_16x16x32_bf16 v[68:71], v[164:167], v[212:215], v[68:71]
	v_mfma_f32_16x16x32_bf16 v[64:67], v[172:175], v[212:215], v[64:67]
	s_setprio 0
	s_barrier
	s_add_i32 m0, s20, s71
	s_add_u32 s12, vcc_lo, 0x80
	s_addc_u32 s13, vcc_hi, 0
	ds_read_b128 v[176:179], v147 offset:49152
	ds_read_b128 v[180:183], v147 offset:50176
	ds_read_b128 v[184:187], v147 offset:51200
	ds_read_b128 v[188:191], v147 offset:52224
	ds_read_b128 v[194:197], v147 offset:53248
	ds_read_b128 v[198:201], v147 offset:54272
	ds_read_b128 v[202:205], v147 offset:55296
	ds_read_b128 v[212:215], v147 offset:56320
	global_load_lds_dwordx4 v192, s[12:13]
	s_add_i32 m0, m0, 0x2000
	s_nop 0
	global_load_lds_dwordx4 v128, s[12:13]
	s_add_u32 s12, s12, s9
	s_addc_u32 s13, s13, 0
	s_add_i32 m0, s36, s71
	s_nop 0
	global_load_lds_dwordx4 v192, s[12:13]
	s_add_i32 m0, m0, 0x2000
	s_nop 0
	global_load_lds_dwordx4 v128, s[12:13]
	s_add_u32 s12, s58, 0x80
	s_addc_u32 s13, s59, 0
	s_mov_b32 m0, s81
	s_nop 0
	global_load_lds_dwordx4 v132, s[12:13]
	s_mov_b32 m0, s82
	s_nop 0
	global_load_lds_dwordx4 v130, s[12:13]
	s_waitcnt vmcnt(8)
	s_waitcnt lgkmcnt(0)
	s_barrier
	s_setprio 1
	v_mfma_f32_16x16x32_bf16 v[60:63], v[138:141], v[176:179], v[60:63]
	v_mfma_f32_16x16x32_bf16 v[56:59], v[152:155], v[176:179], v[56:59]
	v_mfma_f32_16x16x32_bf16 v[44:47], v[138:141], v[184:187], v[44:47]
	v_mfma_f32_16x16x32_bf16 v[40:43], v[152:155], v[184:187], v[40:43]
	v_mfma_f32_16x16x32_bf16 v[28:31], v[138:141], v[194:197], v[28:31]
	v_mfma_f32_16x16x32_bf16 v[24:27], v[152:155], v[194:197], v[24:27]
	v_mfma_f32_16x16x32_bf16 v[12:15], v[138:141], v[202:205], v[12:15]
	v_mfma_f32_16x16x32_bf16 v[8:11], v[152:155], v[202:205], v[8:11]
	v_mfma_f32_16x16x32_bf16 v[60:63], v[148:151], v[180:183], v[60:63]
	v_mfma_f32_16x16x32_bf16 v[56:59], v[156:159], v[180:183], v[56:59]
	v_mfma_f32_16x16x32_bf16 v[44:47], v[148:151], v[188:191], v[44:47]
	v_mfma_f32_16x16x32_bf16 v[40:43], v[156:159], v[188:191], v[40:43]
	v_mfma_f32_16x16x32_bf16 v[28:31], v[148:151], v[198:201], v[28:31]
	v_mfma_f32_16x16x32_bf16 v[24:27], v[156:159], v[198:201], v[24:27]
	v_mfma_f32_16x16x32_bf16 v[12:15], v[148:151], v[212:215], v[12:15]
	v_mfma_f32_16x16x32_bf16 v[8:11], v[156:159], v[212:215], v[8:11]
	v_mfma_f32_16x16x32_bf16 v[52:55], v[160:163], v[176:179], v[52:55]
	v_mfma_f32_16x16x32_bf16 v[48:51], v[168:171], v[176:179], v[48:51]
	v_mfma_f32_16x16x32_bf16 v[36:39], v[160:163], v[184:187], v[36:39]
	v_mfma_f32_16x16x32_bf16 v[32:35], v[168:171], v[184:187], v[32:35]
	v_mfma_f32_16x16x32_bf16 v[20:23], v[160:163], v[194:197], v[20:23]
	v_mfma_f32_16x16x32_bf16 v[16:19], v[168:171], v[194:197], v[16:19]
	v_mfma_f32_16x16x32_bf16 v[4:7], v[160:163], v[202:205], v[4:7]
	v_mfma_f32_16x16x32_bf16 v[0:3], v[168:171], v[202:205], v[0:3]
	v_mfma_f32_16x16x32_bf16 v[52:55], v[164:167], v[180:183], v[52:55]
	v_mfma_f32_16x16x32_bf16 v[48:51], v[172:175], v[180:183], v[48:51]
	v_mfma_f32_16x16x32_bf16 v[36:39], v[164:167], v[188:191], v[36:39]
	v_mfma_f32_16x16x32_bf16 v[32:35], v[172:175], v[188:191], v[32:35]
	v_mfma_f32_16x16x32_bf16 v[20:23], v[164:167], v[198:201], v[20:23]
	v_mfma_f32_16x16x32_bf16 v[16:19], v[172:175], v[198:201], v[16:19]
	v_mfma_f32_16x16x32_bf16 v[4:7], v[164:167], v[212:215], v[4:7]
	v_mfma_f32_16x16x32_bf16 v[0:3], v[172:175], v[212:215], v[0:3]
	s_setprio 0
	s_add_u32 s28, s28, 0x100
	s_addc_u32 s29, s29, 0
	s_add_u32 s18, s18, 0x100
	s_addc_u32 s19, s19, 0
	s_cmp_ge_u32 s21, s83
	s_mov_b32 s20, s21
	s_barrier
	s_cbranch_scc0 .LBB0_113
	s_and_b64 vcc, exec, s[54:55]
	s_cbranch_vccz .LBB0_116

.LBB0_137:
	s_add_i32 s21, s20, 2
	s_add_u32 s12, s28, 0x80
	s_addc_u32 s13, s29, 0
	s_add_i32 s36, 0, 0x10000
	s_cmp_eq_u32 s81, s20
	s_cselect_b32 s55, s5, s13
	s_cselect_b32 s54, s4, s12
	s_cselect_b32 s13, s53, s19
	s_cselect_b32 s12, s52, s18
	s_add_i32 s20, 0, 0x14000
	v_add_u32_e32 v154, s36, v139
	v_add_u32_e32 v170, s20, v139
	ds_read_b128 v[142:145], v154
	ds_read_b128 v[146:149], v154 offset:1024
	ds_read_b128 v[150:153], v154 offset:2048
	ds_read_b128 v[154:157], v154 offset:3072
	ds_read_b128 v[158:161], v170
	ds_read_b128 v[162:165], v170 offset:1024
	ds_read_b128 v[166:169], v170 offset:2048
	ds_read_b128 v[170:173], v170 offset:3072
	s_add_i32 m0, s73, 0xc000
	ds_read_b128 v[174:177], v141
	ds_read_b128 v[178:181], v141 offset:1024
	ds_read_b128 v[182:185], v141 offset:2048
	ds_read_b128 v[186:189], v141 offset:3072
	ds_read_b128 v[194:197], v141 offset:4096
	ds_read_b128 v[198:201], v141 offset:5120
	ds_read_b128 v[202:205], v141 offset:6144
	ds_read_b128 v[212:215], v141 offset:7168
	global_load_lds_dwordx4 v134, s[28:29]
	s_add_i32 m0, s73, 0xe000
	s_nop 0
	global_load_lds_dwordx4 v136, s[28:29]
	s_waitcnt vmcnt(8)
	s_waitcnt lgkmcnt(0)
	s_barrier
	s_setprio 1
	v_mfma_f32_16x16x32_bf16 v[124:127], v[142:145], v[174:177], v[124:127]
	v_mfma_f32_16x16x32_bf16 v[116:119], v[150:153], v[174:177], v[116:119]
	v_mfma_f32_16x16x32_bf16 v[108:111], v[142:145], v[182:185], v[108:111]
	v_mfma_f32_16x16x32_bf16 v[100:103], v[150:153], v[182:185], v[100:103]
	v_mfma_f32_16x16x32_bf16 v[92:95], v[142:145], v[194:197], v[92:95]
	v_mfma_f32_16x16x32_bf16 v[84:87], v[150:153], v[194:197], v[84:87]
	v_mfma_f32_16x16x32_bf16 v[76:79], v[142:145], v[202:205], v[76:79]
	v_mfma_f32_16x16x32_bf16 v[68:71], v[150:153], v[202:205], v[68:71]
	v_mfma_f32_16x16x32_bf16 v[124:127], v[146:149], v[178:181], v[124:127]
	v_mfma_f32_16x16x32_bf16 v[116:119], v[154:157], v[178:181], v[116:119]
	v_mfma_f32_16x16x32_bf16 v[108:111], v[146:149], v[186:189], v[108:111]
	v_mfma_f32_16x16x32_bf16 v[100:103], v[154:157], v[186:189], v[100:103]
	v_mfma_f32_16x16x32_bf16 v[92:95], v[146:149], v[198:201], v[92:95]
	v_mfma_f32_16x16x32_bf16 v[84:87], v[154:157], v[198:201], v[84:87]
	v_mfma_f32_16x16x32_bf16 v[76:79], v[146:149], v[212:215], v[76:79]
	v_mfma_f32_16x16x32_bf16 v[68:71], v[154:157], v[212:215], v[68:71]
	v_mfma_f32_16x16x32_bf16 v[120:123], v[158:161], v[174:177], v[120:123]
	v_mfma_f32_16x16x32_bf16 v[112:115], v[166:169], v[174:177], v[112:115]
	v_mfma_f32_16x16x32_bf16 v[104:107], v[158:161], v[182:185], v[104:107]
	v_mfma_f32_16x16x32_bf16 v[96:99], v[166:169], v[182:185], v[96:99]
	v_mfma_f32_16x16x32_bf16 v[88:91], v[158:161], v[194:197], v[88:91]
	v_mfma_f32_16x16x32_bf16 v[80:83], v[166:169], v[194:197], v[80:83]
	v_mfma_f32_16x16x32_bf16 v[72:75], v[158:161], v[202:205], v[72:75]
	v_mfma_f32_16x16x32_bf16 v[64:67], v[166:169], v[202:205], v[64:67]
	v_mfma_f32_16x16x32_bf16 v[120:123], v[162:165], v[178:181], v[120:123]
	v_mfma_f32_16x16x32_bf16 v[112:115], v[170:173], v[178:181], v[112:115]
	v_mfma_f32_16x16x32_bf16 v[104:107], v[162:165], v[186:189], v[104:107]
	v_mfma_f32_16x16x32_bf16 v[96:99], v[170:173], v[186:189], v[96:99]
	v_mfma_f32_16x16x32_bf16 v[88:91], v[162:165], v[198:201], v[88:91]
	v_mfma_f32_16x16x32_bf16 v[80:83], v[170:173], v[198:201], v[80:83]
	v_mfma_f32_16x16x32_bf16 v[72:75], v[162:165], v[212:215], v[72:75]
	v_mfma_f32_16x16x32_bf16 v[64:67], v[170:173], v[212:215], v[64:67]
	s_setprio 0
	s_barrier
	s_add_i32 s36, s36, s57
	s_mov_b64 vcc, s[12:13]
	s_mov_b32 m0, s36
	ds_read_b128 v[174:177], v141 offset:16384
	ds_read_b128 v[178:181], v141 offset:17408
	ds_read_b128 v[182:185], v141 offset:18432
	ds_read_b128 v[186:189], v141 offset:19456
	ds_read_b128 v[194:197], v141 offset:20480
	ds_read_b128 v[198:201], v141 offset:21504
	ds_read_b128 v[202:205], v141 offset:22528
	ds_read_b128 v[212:215], v141 offset:23552
	global_load_lds_dwordx4 v192, s[12:13]
	s_add_i32 m0, s36, 0x2000
	s_add_i32 s20, s20, s57
	global_load_lds_dwordx4 v128, s[12:13]
	s_add_u32 s12, s12, s9
	s_addc_u32 s13, s13, 0
	s_mov_b32 m0, s20
	s_nop 0
	global_load_lds_dwordx4 v192, s[12:13]
	s_add_i32 m0, s20, 0x2000
	s_nop 0
	global_load_lds_dwordx4 v128, s[12:13]
	s_mov_b32 m0, s73
	s_nop 0
	global_load_lds_dwordx4 v132, s[54:55]
	s_mov_b32 m0, s74
	s_nop 0
	global_load_lds_dwordx4 v130, s[54:55]
	s_waitcnt vmcnt(8)
	s_waitcnt lgkmcnt(0)
	s_barrier
	s_setprio 1
	v_mfma_f32_16x16x32_bf16 v[60:63], v[142:145], v[174:177], v[60:63]
	v_mfma_f32_16x16x32_bf16 v[52:55], v[150:153], v[174:177], v[52:55]
	v_mfma_f32_16x16x32_bf16 v[44:47], v[142:145], v[182:185], v[44:47]
	v_mfma_f32_16x16x32_bf16 v[36:39], v[150:153], v[182:185], v[36:39]
	v_mfma_f32_16x16x32_bf16 v[28:31], v[142:145], v[194:197], v[28:31]
	v_mfma_f32_16x16x32_bf16 v[20:23], v[150:153], v[194:197], v[20:23]
	v_mfma_f32_16x16x32_bf16 v[12:15], v[142:145], v[202:205], v[12:15]
	v_mfma_f32_16x16x32_bf16 v[4:7], v[150:153], v[202:205], v[4:7]
	v_mfma_f32_16x16x32_bf16 v[60:63], v[146:149], v[178:181], v[60:63]
	v_mfma_f32_16x16x32_bf16 v[52:55], v[154:157], v[178:181], v[52:55]
	v_mfma_f32_16x16x32_bf16 v[44:47], v[146:149], v[186:189], v[44:47]
	v_mfma_f32_16x16x32_bf16 v[36:39], v[154:157], v[186:189], v[36:39]
	v_mfma_f32_16x16x32_bf16 v[28:31], v[146:149], v[198:201], v[28:31]
	v_mfma_f32_16x16x32_bf16 v[20:23], v[154:157], v[198:201], v[20:23]
	v_mfma_f32_16x16x32_bf16 v[12:15], v[146:149], v[212:215], v[12:15]
	v_mfma_f32_16x16x32_bf16 v[4:7], v[154:157], v[212:215], v[4:7]
	v_mfma_f32_16x16x32_bf16 v[56:59], v[158:161], v[174:177], v[56:59]
	v_mfma_f32_16x16x32_bf16 v[48:51], v[166:169], v[174:177], v[48:51]
	v_mfma_f32_16x16x32_bf16 v[40:43], v[158:161], v[182:185], v[40:43]
	v_mfma_f32_16x16x32_bf16 v[32:35], v[166:169], v[182:185], v[32:35]
	v_mfma_f32_16x16x32_bf16 v[24:27], v[158:161], v[194:197], v[24:27]
	v_mfma_f32_16x16x32_bf16 v[16:19], v[166:169], v[194:197], v[16:19]
	v_mfma_f32_16x16x32_bf16 v[8:11], v[158:161], v[202:205], v[8:11]
	v_mfma_f32_16x16x32_bf16 v[0:3], v[166:169], v[202:205], v[0:3]
	v_mfma_f32_16x16x32_bf16 v[56:59], v[162:165], v[178:181], v[56:59]
	v_mfma_f32_16x16x32_bf16 v[48:51], v[170:173], v[178:181], v[48:51]
	v_mfma_f32_16x16x32_bf16 v[40:43], v[162:165], v[186:189], v[40:43]
	v_mfma_f32_16x16x32_bf16 v[32:35], v[170:173], v[186:189], v[32:35]
	v_mfma_f32_16x16x32_bf16 v[24:27], v[162:165], v[198:201], v[24:27]
	v_mfma_f32_16x16x32_bf16 v[16:19], v[170:173], v[198:201], v[16:19]
	v_mfma_f32_16x16x32_bf16 v[8:11], v[162:165], v[212:215], v[8:11]
	v_mfma_f32_16x16x32_bf16 v[0:3], v[170:173], v[212:215], v[0:3]
	s_setprio 0
	s_barrier
	s_add_i32 s20, 0, 0x18000
	s_add_i32 s36, 0, 0x1c000
	v_add_u32_e32 v154, s20, v139
	v_add_u32_e32 v170, s36, v139
	ds_read_b128 v[142:145], v154
	ds_read_b128 v[146:149], v154 offset:1024
	ds_read_b128 v[150:153], v154 offset:2048
	ds_read_b128 v[154:157], v154 offset:3072
	ds_read_b128 v[158:161], v170
	ds_read_b128 v[162:165], v170 offset:1024
	ds_read_b128 v[166:169], v170 offset:2048
	ds_read_b128 v[170:173], v170 offset:3072
	s_add_u32 s12, s54, s34
	s_addc_u32 s13, s55, 0
	s_mov_b32 m0, s75
	ds_read_b128 v[174:177], v141 offset:32768
	ds_read_b128 v[178:181], v141 offset:33792
	ds_read_b128 v[182:185], v141 offset:34816
	ds_read_b128 v[186:189], v141 offset:35840
	ds_read_b128 v[194:197], v141 offset:36864
	ds_read_b128 v[198:201], v141 offset:37888
	ds_read_b128 v[202:205], v141 offset:38912
	ds_read_b128 v[212:215], v141 offset:39936
	global_load_lds_dwordx4 v132, s[12:13]
	s_mov_b32 m0, s76
	s_nop 0
	global_load_lds_dwordx4 v130, s[12:13]
	s_waitcnt vmcnt(8)
	s_waitcnt lgkmcnt(0)
	s_barrier
	s_setprio 1
	v_mfma_f32_16x16x32_bf16 v[124:127], v[142:145], v[174:177], v[124:127]
	v_mfma_f32_16x16x32_bf16 v[116:119], v[150:153], v[174:177], v[116:119]
	v_mfma_f32_16x16x32_bf16 v[108:111], v[142:145], v[182:185], v[108:111]
	v_mfma_f32_16x16x32_bf16 v[100:103], v[150:153], v[182:185], v[100:103]
	v_mfma_f32_16x16x32_bf16 v[92:95], v[142:145], v[194:197], v[92:95]
	v_mfma_f32_16x16x32_bf16 v[84:87], v[150:153], v[194:197], v[84:87]
	v_mfma_f32_16x16x32_bf16 v[76:79], v[142:145], v[202:205], v[76:79]
	v_mfma_f32_16x16x32_bf16 v[68:71], v[150:153], v[202:205], v[68:71]
	v_mfma_f32_16x16x32_bf16 v[124:127], v[146:149], v[178:181], v[124:127]
	v_mfma_f32_16x16x32_bf16 v[116:119], v[154:157], v[178:181], v[116:119]
	v_mfma_f32_16x16x32_bf16 v[108:111], v[146:149], v[186:189], v[108:111]
	v_mfma_f32_16x16x32_bf16 v[100:103], v[154:157], v[186:189], v[100:103]
	v_mfma_f32_16x16x32_bf16 v[92:95], v[146:149], v[198:201], v[92:95]
	v_mfma_f32_16x16x32_bf16 v[84:87], v[154:157], v[198:201], v[84:87]
	v_mfma_f32_16x16x32_bf16 v[76:79], v[146:149], v[212:215], v[76:79]
	v_mfma_f32_16x16x32_bf16 v[68:71], v[154:157], v[212:215], v[68:71]
	v_mfma_f32_16x16x32_bf16 v[120:123], v[158:161], v[174:177], v[120:123]
	v_mfma_f32_16x16x32_bf16 v[112:115], v[166:169], v[174:177], v[112:115]
	v_mfma_f32_16x16x32_bf16 v[104:107], v[158:161], v[182:185], v[104:107]
	v_mfma_f32_16x16x32_bf16 v[96:99], v[166:169], v[182:185], v[96:99]
	v_mfma_f32_16x16x32_bf16 v[88:91], v[158:161], v[194:197], v[88:91]
	v_mfma_f32_16x16x32_bf16 v[80:83], v[166:169], v[194:197], v[80:83]
	v_mfma_f32_16x16x32_bf16 v[72:75], v[158:161], v[202:205], v[72:75]
	v_mfma_f32_16x16x32_bf16 v[64:67], v[166:169], v[202:205], v[64:67]
	v_mfma_f32_16x16x32_bf16 v[120:123], v[162:165], v[178:181], v[120:123]
	v_mfma_f32_16x16x32_bf16 v[112:115], v[170:173], v[178:181], v[112:115]
	v_mfma_f32_16x16x32_bf16 v[104:107], v[162:165], v[186:189], v[104:107]
	v_mfma_f32_16x16x32_bf16 v[96:99], v[170:173], v[186:189], v[96:99]
	v_mfma_f32_16x16x32_bf16 v[88:91], v[162:165], v[198:201], v[88:91]
	v_mfma_f32_16x16x32_bf16 v[80:83], v[170:173], v[198:201], v[80:83]
	v_mfma_f32_16x16x32_bf16 v[72:75], v[162:165], v[212:215], v[72:75]
	v_mfma_f32_16x16x32_bf16 v[64:67], v[170:173], v[212:215], v[64:67]
	s_setprio 0
	s_barrier
	s_add_i32 m0, s20, s57
	s_add_u32 s12, vcc_lo, 0x80
	s_addc_u32 s13, vcc_hi, 0
	ds_read_b128 v[174:177], v141 offset:49152
	ds_read_b128 v[178:181], v141 offset:50176
	ds_read_b128 v[182:185], v141 offset:51200
	ds_read_b128 v[186:189], v141 offset:52224
	ds_read_b128 v[194:197], v141 offset:53248
	ds_read_b128 v[198:201], v141 offset:54272
	ds_read_b128 v[202:205], v141 offset:55296
	ds_read_b128 v[212:215], v141 offset:56320
	global_load_lds_dwordx4 v192, s[12:13]
	s_add_i32 m0, m0, 0x2000
	s_nop 0
	global_load_lds_dwordx4 v128, s[12:13]
	s_add_u32 s12, s12, s9
	s_addc_u32 s13, s13, 0
	s_add_i32 m0, s36, s57
	s_nop 0
	global_load_lds_dwordx4 v192, s[12:13]
	s_add_i32 m0, m0, 0x2000
	s_nop 0
	global_load_lds_dwordx4 v128, s[12:13]
	s_add_u32 s12, s54, 0x80
	s_addc_u32 s13, s55, 0
	s_mov_b32 m0, s77
	s_nop 0
	global_load_lds_dwordx4 v132, s[12:13]
	s_mov_b32 m0, s78
	s_nop 0
	global_load_lds_dwordx4 v130, s[12:13]
	s_waitcnt vmcnt(8)
	s_waitcnt lgkmcnt(0)
	s_barrier
	s_setprio 1
	v_mfma_f32_16x16x32_bf16 v[60:63], v[142:145], v[174:177], v[60:63]
	v_mfma_f32_16x16x32_bf16 v[52:55], v[150:153], v[174:177], v[52:55]
	v_mfma_f32_16x16x32_bf16 v[44:47], v[142:145], v[182:185], v[44:47]
	v_mfma_f32_16x16x32_bf16 v[36:39], v[150:153], v[182:185], v[36:39]
	v_mfma_f32_16x16x32_bf16 v[28:31], v[142:145], v[194:197], v[28:31]
	v_mfma_f32_16x16x32_bf16 v[20:23], v[150:153], v[194:197], v[20:23]
	v_mfma_f32_16x16x32_bf16 v[12:15], v[142:145], v[202:205], v[12:15]
	v_mfma_f32_16x16x32_bf16 v[4:7], v[150:153], v[202:205], v[4:7]
	v_mfma_f32_16x16x32_bf16 v[60:63], v[146:149], v[178:181], v[60:63]
	v_mfma_f32_16x16x32_bf16 v[52:55], v[154:157], v[178:181], v[52:55]
	v_mfma_f32_16x16x32_bf16 v[44:47], v[146:149], v[186:189], v[44:47]
	v_mfma_f32_16x16x32_bf16 v[36:39], v[154:157], v[186:189], v[36:39]
	v_mfma_f32_16x16x32_bf16 v[28:31], v[146:149], v[198:201], v[28:31]
	v_mfma_f32_16x16x32_bf16 v[20:23], v[154:157], v[198:201], v[20:23]
	v_mfma_f32_16x16x32_bf16 v[12:15], v[146:149], v[212:215], v[12:15]
	v_mfma_f32_16x16x32_bf16 v[4:7], v[154:157], v[212:215], v[4:7]
	v_mfma_f32_16x16x32_bf16 v[56:59], v[158:161], v[174:177], v[56:59]
	v_mfma_f32_16x16x32_bf16 v[48:51], v[166:169], v[174:177], v[48:51]
	v_mfma_f32_16x16x32_bf16 v[40:43], v[158:161], v[182:185], v[40:43]
	v_mfma_f32_16x16x32_bf16 v[32:35], v[166:169], v[182:185], v[32:35]
	v_mfma_f32_16x16x32_bf16 v[24:27], v[158:161], v[194:197], v[24:27]
	v_mfma_f32_16x16x32_bf16 v[16:19], v[166:169], v[194:197], v[16:19]
	v_mfma_f32_16x16x32_bf16 v[8:11], v[158:161], v[202:205], v[8:11]
	v_mfma_f32_16x16x32_bf16 v[0:3], v[166:169], v[202:205], v[0:3]
	v_mfma_f32_16x16x32_bf16 v[56:59], v[162:165], v[178:181], v[56:59]
	v_mfma_f32_16x16x32_bf16 v[48:51], v[170:173], v[178:181], v[48:51]
	v_mfma_f32_16x16x32_bf16 v[40:43], v[162:165], v[186:189], v[40:43]
	v_mfma_f32_16x16x32_bf16 v[32:35], v[170:173], v[186:189], v[32:35]
	v_mfma_f32_16x16x32_bf16 v[24:27], v[162:165], v[198:201], v[24:27]
	v_mfma_f32_16x16x32_bf16 v[16:19], v[170:173], v[198:201], v[16:19]
	v_mfma_f32_16x16x32_bf16 v[8:11], v[162:165], v[212:215], v[8:11]
	v_mfma_f32_16x16x32_bf16 v[0:3], v[170:173], v[212:215], v[0:3]
	s_setprio 0
	s_add_u32 s28, s28, 0x100
	s_addc_u32 s29, s29, 0
	s_add_u32 s18, s18, 0x100
	s_addc_u32 s19, s19, 0
	s_cmp_ge_u32 s21, s79
	s_mov_b32 s20, s21
	s_barrier
	s_cbranch_scc0 .LBB0_137
	s_and_b64 vcc, exec, s[50:51]
	s_cbranch_vccz .LBB0_140

.LBB0_161:
	s_add_i32 s21, s20, 2
	s_add_u32 s12, s28, 0x80
	s_addc_u32 s13, s29, 0
	s_add_i32 s36, 0, 0x10000
	s_cmp_eq_u32 s85, s20
	s_cselect_b32 s59, s5, s13
	s_cselect_b32 s58, s4, s12
	v_add_u32_e32 v138, s36, v141
	s_cselect_b32 s13, s57, s19
	s_cselect_b32 s12, s56, s18
	s_add_i32 s20, 0, 0x14000
	ds_read_b128 v[148:151], v138
	ds_read_b128 v[152:155], v138 offset:1024
	ds_read_b128 v[156:159], v138 offset:2048
	ds_read_b128 v[160:163], v138 offset:3072
	v_add_u32_e32 v138, s20, v141
	ds_read_b128 v[164:167], v138
	ds_read_b128 v[168:171], v138 offset:1024
	ds_read_b128 v[172:175], v138 offset:2048
	ds_read_b128 v[176:179], v138 offset:3072
	s_add_i32 m0, s78, 0xc000
	ds_read_b128 v[180:183], v147
	ds_read_b128 v[184:187], v147 offset:1024
	ds_read_b128 v[188:191], v147 offset:2048
	ds_read_b128 v[194:197], v147 offset:3072
	ds_read_b128 v[198:201], v147 offset:4096
	ds_read_b128 v[202:205], v147 offset:5120
	ds_read_b128 v[212:215], v147 offset:6144
	ds_read_b128 v[242:245], v147 offset:7168
	global_load_lds_dwordx4 v134, s[28:29]
	s_add_i32 m0, s78, 0xe000
	s_nop 0
	global_load_lds_dwordx4 v136, s[28:29]
	s_waitcnt vmcnt(8)
	s_waitcnt lgkmcnt(0)
	s_barrier
	s_setprio 1
	v_mfma_f32_16x16x32_bf16 v[124:127], v[148:151], v[180:183], v[124:127]
	v_mfma_f32_16x16x32_bf16 v[120:123], v[156:159], v[180:183], v[120:123]
	v_mfma_f32_16x16x32_bf16 v[108:111], v[148:151], v[188:191], v[108:111]
	v_mfma_f32_16x16x32_bf16 v[104:107], v[156:159], v[188:191], v[104:107]
	v_mfma_f32_16x16x32_bf16 v[92:95], v[148:151], v[198:201], v[92:95]
	v_mfma_f32_16x16x32_bf16 v[88:91], v[156:159], v[198:201], v[88:91]
	v_mfma_f32_16x16x32_bf16 v[76:79], v[148:151], v[212:215], v[76:79]
	v_mfma_f32_16x16x32_bf16 v[72:75], v[156:159], v[212:215], v[72:75]
	v_mfma_f32_16x16x32_bf16 v[124:127], v[152:155], v[184:187], v[124:127]
	v_mfma_f32_16x16x32_bf16 v[120:123], v[160:163], v[184:187], v[120:123]
	v_mfma_f32_16x16x32_bf16 v[108:111], v[152:155], v[194:197], v[108:111]
	v_mfma_f32_16x16x32_bf16 v[104:107], v[160:163], v[194:197], v[104:107]
	v_mfma_f32_16x16x32_bf16 v[92:95], v[152:155], v[202:205], v[92:95]
	v_mfma_f32_16x16x32_bf16 v[88:91], v[160:163], v[202:205], v[88:91]
	v_mfma_f32_16x16x32_bf16 v[76:79], v[152:155], v[242:245], v[76:79]
	v_mfma_f32_16x16x32_bf16 v[72:75], v[160:163], v[242:245], v[72:75]
	v_mfma_f32_16x16x32_bf16 v[116:119], v[164:167], v[180:183], v[116:119]
	v_mfma_f32_16x16x32_bf16 v[112:115], v[172:175], v[180:183], v[112:115]
	v_mfma_f32_16x16x32_bf16 v[100:103], v[164:167], v[188:191], v[100:103]
	v_mfma_f32_16x16x32_bf16 v[96:99], v[172:175], v[188:191], v[96:99]
	v_mfma_f32_16x16x32_bf16 v[84:87], v[164:167], v[198:201], v[84:87]
	v_mfma_f32_16x16x32_bf16 v[80:83], v[172:175], v[198:201], v[80:83]
	v_mfma_f32_16x16x32_bf16 v[68:71], v[164:167], v[212:215], v[68:71]
	v_mfma_f32_16x16x32_bf16 v[64:67], v[172:175], v[212:215], v[64:67]
	v_mfma_f32_16x16x32_bf16 v[116:119], v[168:171], v[184:187], v[116:119]
	v_mfma_f32_16x16x32_bf16 v[112:115], v[176:179], v[184:187], v[112:115]
	v_mfma_f32_16x16x32_bf16 v[100:103], v[168:171], v[194:197], v[100:103]
	v_mfma_f32_16x16x32_bf16 v[96:99], v[176:179], v[194:197], v[96:99]
	v_mfma_f32_16x16x32_bf16 v[84:87], v[168:171], v[202:205], v[84:87]
	v_mfma_f32_16x16x32_bf16 v[80:83], v[176:179], v[202:205], v[80:83]
	v_mfma_f32_16x16x32_bf16 v[68:71], v[168:171], v[242:245], v[68:71]
	v_mfma_f32_16x16x32_bf16 v[64:67], v[176:179], v[242:245], v[64:67]
	s_setprio 0
	s_barrier
	s_add_i32 s36, s36, s72
	s_mov_b64 vcc, s[12:13]
	s_mov_b32 m0, s36
	ds_read_b128 v[180:183], v147 offset:16384
	ds_read_b128 v[184:187], v147 offset:17408
	ds_read_b128 v[188:191], v147 offset:18432
	ds_read_b128 v[194:197], v147 offset:19456
	ds_read_b128 v[198:201], v147 offset:20480
	ds_read_b128 v[202:205], v147 offset:21504
	ds_read_b128 v[212:215], v147 offset:22528
	ds_read_b128 v[242:245], v147 offset:23552
	global_load_lds_dwordx4 v192, s[12:13]
	s_add_i32 m0, s36, 0x2000
	s_add_i32 s20, s20, s72
	global_load_lds_dwordx4 v128, s[12:13]
	s_add_u32 s12, s12, s70
	s_addc_u32 s13, s13, 0
	s_mov_b32 m0, s20
	s_nop 0
	global_load_lds_dwordx4 v192, s[12:13]
	s_add_i32 m0, s20, 0x2000
	s_nop 0
	global_load_lds_dwordx4 v128, s[12:13]
	s_mov_b32 m0, s78
	s_nop 0
	global_load_lds_dwordx4 v132, s[58:59]
	s_mov_b32 m0, s79
	s_nop 0
	global_load_lds_dwordx4 v130, s[58:59]
	s_waitcnt vmcnt(8)
	s_waitcnt lgkmcnt(0)
	s_barrier
	s_setprio 1
	v_mfma_f32_16x16x32_bf16 v[60:63], v[148:151], v[180:183], v[60:63]
	v_mfma_f32_16x16x32_bf16 v[56:59], v[156:159], v[180:183], v[56:59]
	v_mfma_f32_16x16x32_bf16 v[44:47], v[148:151], v[188:191], v[44:47]
	v_mfma_f32_16x16x32_bf16 v[40:43], v[156:159], v[188:191], v[40:43]
	v_mfma_f32_16x16x32_bf16 v[28:31], v[148:151], v[198:201], v[28:31]
	v_mfma_f32_16x16x32_bf16 v[24:27], v[156:159], v[198:201], v[24:27]
	v_mfma_f32_16x16x32_bf16 v[12:15], v[148:151], v[212:215], v[12:15]
	v_mfma_f32_16x16x32_bf16 v[8:11], v[156:159], v[212:215], v[8:11]
	v_mfma_f32_16x16x32_bf16 v[60:63], v[152:155], v[184:187], v[60:63]
	v_mfma_f32_16x16x32_bf16 v[56:59], v[160:163], v[184:187], v[56:59]
	v_mfma_f32_16x16x32_bf16 v[44:47], v[152:155], v[194:197], v[44:47]
	v_mfma_f32_16x16x32_bf16 v[40:43], v[160:163], v[194:197], v[40:43]
	v_mfma_f32_16x16x32_bf16 v[28:31], v[152:155], v[202:205], v[28:31]
	v_mfma_f32_16x16x32_bf16 v[24:27], v[160:163], v[202:205], v[24:27]
	v_mfma_f32_16x16x32_bf16 v[12:15], v[152:155], v[242:245], v[12:15]
	v_mfma_f32_16x16x32_bf16 v[8:11], v[160:163], v[242:245], v[8:11]
	v_mfma_f32_16x16x32_bf16 v[52:55], v[164:167], v[180:183], v[52:55]
	v_mfma_f32_16x16x32_bf16 v[48:51], v[172:175], v[180:183], v[48:51]
	v_mfma_f32_16x16x32_bf16 v[36:39], v[164:167], v[188:191], v[36:39]
	v_mfma_f32_16x16x32_bf16 v[32:35], v[172:175], v[188:191], v[32:35]
	v_mfma_f32_16x16x32_bf16 v[20:23], v[164:167], v[198:201], v[20:23]
	v_mfma_f32_16x16x32_bf16 v[16:19], v[172:175], v[198:201], v[16:19]
	v_mfma_f32_16x16x32_bf16 v[4:7], v[164:167], v[212:215], v[4:7]
	v_mfma_f32_16x16x32_bf16 v[0:3], v[172:175], v[212:215], v[0:3]
	v_mfma_f32_16x16x32_bf16 v[52:55], v[168:171], v[184:187], v[52:55]
	v_mfma_f32_16x16x32_bf16 v[48:51], v[176:179], v[184:187], v[48:51]
	v_mfma_f32_16x16x32_bf16 v[36:39], v[168:171], v[194:197], v[36:39]
	v_mfma_f32_16x16x32_bf16 v[32:35], v[176:179], v[194:197], v[32:35]
	v_mfma_f32_16x16x32_bf16 v[20:23], v[168:171], v[202:205], v[20:23]
	v_mfma_f32_16x16x32_bf16 v[16:19], v[176:179], v[202:205], v[16:19]
	v_mfma_f32_16x16x32_bf16 v[4:7], v[168:171], v[242:245], v[4:7]
	v_mfma_f32_16x16x32_bf16 v[0:3], v[176:179], v[242:245], v[0:3]
	s_setprio 0
	s_barrier
	s_add_i32 s20, 0, 0x18000
	v_add_u32_e32 v138, s20, v141
	s_add_i32 s36, 0, 0x1c000
	ds_read_b128 v[148:151], v138
	ds_read_b128 v[152:155], v138 offset:1024
	ds_read_b128 v[156:159], v138 offset:2048
	ds_read_b128 v[160:163], v138 offset:3072
	v_add_u32_e32 v138, s36, v141
	ds_read_b128 v[164:167], v138
	ds_read_b128 v[168:171], v138 offset:1024
	ds_read_b128 v[172:175], v138 offset:2048
	ds_read_b128 v[176:179], v138 offset:3072
	s_add_u32 s12, s58, s34
	s_addc_u32 s13, s59, 0
	s_mov_b32 m0, s80
	ds_read_b128 v[180:183], v147 offset:32768
	ds_read_b128 v[184:187], v147 offset:33792
	ds_read_b128 v[188:191], v147 offset:34816
	ds_read_b128 v[194:197], v147 offset:35840
	ds_read_b128 v[198:201], v147 offset:36864
	ds_read_b128 v[202:205], v147 offset:37888
	ds_read_b128 v[212:215], v147 offset:38912
	ds_read_b128 v[242:245], v147 offset:39936
	global_load_lds_dwordx4 v132, s[12:13]
	s_mov_b32 m0, s81
	s_nop 0
	global_load_lds_dwordx4 v130, s[12:13]
	s_waitcnt vmcnt(8)
	s_waitcnt lgkmcnt(0)
	s_barrier
	s_setprio 1
	v_mfma_f32_16x16x32_bf16 v[124:127], v[148:151], v[180:183], v[124:127]
	v_mfma_f32_16x16x32_bf16 v[120:123], v[156:159], v[180:183], v[120:123]
	v_mfma_f32_16x16x32_bf16 v[108:111], v[148:151], v[188:191], v[108:111]
	v_mfma_f32_16x16x32_bf16 v[104:107], v[156:159], v[188:191], v[104:107]
	v_mfma_f32_16x16x32_bf16 v[92:95], v[148:151], v[198:201], v[92:95]
	v_mfma_f32_16x16x32_bf16 v[88:91], v[156:159], v[198:201], v[88:91]
	v_mfma_f32_16x16x32_bf16 v[76:79], v[148:151], v[212:215], v[76:79]
	v_mfma_f32_16x16x32_bf16 v[72:75], v[156:159], v[212:215], v[72:75]
	v_mfma_f32_16x16x32_bf16 v[124:127], v[152:155], v[184:187], v[124:127]
	v_mfma_f32_16x16x32_bf16 v[120:123], v[160:163], v[184:187], v[120:123]
	v_mfma_f32_16x16x32_bf16 v[108:111], v[152:155], v[194:197], v[108:111]
	v_mfma_f32_16x16x32_bf16 v[104:107], v[160:163], v[194:197], v[104:107]
	v_mfma_f32_16x16x32_bf16 v[92:95], v[152:155], v[202:205], v[92:95]
	v_mfma_f32_16x16x32_bf16 v[88:91], v[160:163], v[202:205], v[88:91]
	v_mfma_f32_16x16x32_bf16 v[76:79], v[152:155], v[242:245], v[76:79]
	v_mfma_f32_16x16x32_bf16 v[72:75], v[160:163], v[242:245], v[72:75]
	v_mfma_f32_16x16x32_bf16 v[116:119], v[164:167], v[180:183], v[116:119]
	v_mfma_f32_16x16x32_bf16 v[112:115], v[172:175], v[180:183], v[112:115]
	v_mfma_f32_16x16x32_bf16 v[100:103], v[164:167], v[188:191], v[100:103]
	v_mfma_f32_16x16x32_bf16 v[96:99], v[172:175], v[188:191], v[96:99]
	v_mfma_f32_16x16x32_bf16 v[84:87], v[164:167], v[198:201], v[84:87]
	v_mfma_f32_16x16x32_bf16 v[80:83], v[172:175], v[198:201], v[80:83]
	v_mfma_f32_16x16x32_bf16 v[68:71], v[164:167], v[212:215], v[68:71]
	v_mfma_f32_16x16x32_bf16 v[64:67], v[172:175], v[212:215], v[64:67]
	v_mfma_f32_16x16x32_bf16 v[116:119], v[168:171], v[184:187], v[116:119]
	v_mfma_f32_16x16x32_bf16 v[112:115], v[176:179], v[184:187], v[112:115]
	v_mfma_f32_16x16x32_bf16 v[100:103], v[168:171], v[194:197], v[100:103]
	v_mfma_f32_16x16x32_bf16 v[96:99], v[176:179], v[194:197], v[96:99]
	v_mfma_f32_16x16x32_bf16 v[84:87], v[168:171], v[202:205], v[84:87]
	v_mfma_f32_16x16x32_bf16 v[80:83], v[176:179], v[202:205], v[80:83]
	v_mfma_f32_16x16x32_bf16 v[68:71], v[168:171], v[242:245], v[68:71]
	v_mfma_f32_16x16x32_bf16 v[64:67], v[176:179], v[242:245], v[64:67]
	s_setprio 0
	s_barrier
	s_add_i32 m0, s20, s72
	s_add_u32 s12, vcc_lo, 0x80
	s_addc_u32 s13, vcc_hi, 0
	ds_read_b128 v[180:183], v147 offset:49152
	ds_read_b128 v[184:187], v147 offset:50176
	ds_read_b128 v[188:191], v147 offset:51200
	ds_read_b128 v[194:197], v147 offset:52224
	ds_read_b128 v[198:201], v147 offset:53248
	ds_read_b128 v[202:205], v147 offset:54272
	ds_read_b128 v[212:215], v147 offset:55296
	ds_read_b128 v[242:245], v147 offset:56320
	global_load_lds_dwordx4 v192, s[12:13]
	s_add_i32 m0, m0, 0x2000
	s_nop 0
	global_load_lds_dwordx4 v128, s[12:13]
	s_add_u32 s12, s12, s70
	s_addc_u32 s13, s13, 0
	s_add_i32 m0, s36, s72
	s_nop 0
	global_load_lds_dwordx4 v192, s[12:13]
	s_add_i32 m0, m0, 0x2000
	s_nop 0
	global_load_lds_dwordx4 v128, s[12:13]
	s_add_u32 s12, s58, 0x80
	s_addc_u32 s13, s59, 0
	s_mov_b32 m0, s82
	s_nop 0
	global_load_lds_dwordx4 v132, s[12:13]
	s_mov_b32 m0, s83
	s_nop 0
	global_load_lds_dwordx4 v130, s[12:13]
	s_waitcnt vmcnt(8)
	s_waitcnt lgkmcnt(0)
	s_barrier
	s_setprio 1
	v_mfma_f32_16x16x32_bf16 v[60:63], v[148:151], v[180:183], v[60:63]
	v_mfma_f32_16x16x32_bf16 v[56:59], v[156:159], v[180:183], v[56:59]
	v_mfma_f32_16x16x32_bf16 v[44:47], v[148:151], v[188:191], v[44:47]
	v_mfma_f32_16x16x32_bf16 v[40:43], v[156:159], v[188:191], v[40:43]
	v_mfma_f32_16x16x32_bf16 v[28:31], v[148:151], v[198:201], v[28:31]
	v_mfma_f32_16x16x32_bf16 v[24:27], v[156:159], v[198:201], v[24:27]
	v_mfma_f32_16x16x32_bf16 v[12:15], v[148:151], v[212:215], v[12:15]
	v_mfma_f32_16x16x32_bf16 v[8:11], v[156:159], v[212:215], v[8:11]
	v_mfma_f32_16x16x32_bf16 v[60:63], v[152:155], v[184:187], v[60:63]
	v_mfma_f32_16x16x32_bf16 v[56:59], v[160:163], v[184:187], v[56:59]
	v_mfma_f32_16x16x32_bf16 v[44:47], v[152:155], v[194:197], v[44:47]
	v_mfma_f32_16x16x32_bf16 v[40:43], v[160:163], v[194:197], v[40:43]
	v_mfma_f32_16x16x32_bf16 v[28:31], v[152:155], v[202:205], v[28:31]
	v_mfma_f32_16x16x32_bf16 v[24:27], v[160:163], v[202:205], v[24:27]
	v_mfma_f32_16x16x32_bf16 v[12:15], v[152:155], v[242:245], v[12:15]
	v_mfma_f32_16x16x32_bf16 v[8:11], v[160:163], v[242:245], v[8:11]
	v_mfma_f32_16x16x32_bf16 v[52:55], v[164:167], v[180:183], v[52:55]
	v_mfma_f32_16x16x32_bf16 v[48:51], v[172:175], v[180:183], v[48:51]
	v_mfma_f32_16x16x32_bf16 v[36:39], v[164:167], v[188:191], v[36:39]
	v_mfma_f32_16x16x32_bf16 v[32:35], v[172:175], v[188:191], v[32:35]
	v_mfma_f32_16x16x32_bf16 v[20:23], v[164:167], v[198:201], v[20:23]
	v_mfma_f32_16x16x32_bf16 v[16:19], v[172:175], v[198:201], v[16:19]
	v_mfma_f32_16x16x32_bf16 v[4:7], v[164:167], v[212:215], v[4:7]
	v_mfma_f32_16x16x32_bf16 v[0:3], v[172:175], v[212:215], v[0:3]
	v_mfma_f32_16x16x32_bf16 v[52:55], v[168:171], v[184:187], v[52:55]
	v_mfma_f32_16x16x32_bf16 v[48:51], v[176:179], v[184:187], v[48:51]
	v_mfma_f32_16x16x32_bf16 v[36:39], v[168:171], v[194:197], v[36:39]
	v_mfma_f32_16x16x32_bf16 v[32:35], v[176:179], v[194:197], v[32:35]
	v_mfma_f32_16x16x32_bf16 v[20:23], v[168:171], v[202:205], v[20:23]
	v_mfma_f32_16x16x32_bf16 v[16:19], v[176:179], v[202:205], v[16:19]
	v_mfma_f32_16x16x32_bf16 v[4:7], v[168:171], v[242:245], v[4:7]
	v_mfma_f32_16x16x32_bf16 v[0:3], v[176:179], v[242:245], v[0:3]
	s_setprio 0
	s_add_u32 s28, s28, 0x100
	s_addc_u32 s29, s29, 0
	s_add_u32 s18, s18, 0x100
	s_addc_u32 s19, s19, 0
	s_cmp_ge_u32 s21, s84
	s_mov_b32 s20, s21
	s_barrier
	s_cbranch_scc0 .LBB0_161
	s_and_b64 vcc, exec, s[50:51]
	s_cbranch_vccz .LBB0_164

.LBB0_188:
	s_add_i32 s21, s20, 2
	s_add_u32 s12, s28, 0x80
	s_addc_u32 s13, s29, 0
	s_add_i32 s36, 0, 0x10000
	s_cmp_eq_u32 s67, s20
	s_cselect_b32 s57, s5, s13
	s_cselect_b32 s56, s4, s12
	s_cselect_b32 s13, s55, s19
	s_cselect_b32 s12, s54, s18
	s_add_i32 s20, 0, 0x14000
	v_add_u32_e32 v154, s36, v139
	v_add_u32_e32 v170, s20, v139
	ds_read_b128 v[142:145], v154
	ds_read_b128 v[146:149], v154 offset:1024
	ds_read_b128 v[150:153], v154 offset:2048
	ds_read_b128 v[154:157], v154 offset:3072
	ds_read_b128 v[158:161], v170
	ds_read_b128 v[162:165], v170 offset:1024
	ds_read_b128 v[166:169], v170 offset:2048
	ds_read_b128 v[170:173], v170 offset:3072
	s_add_i32 m0, s68, 0xc000
	ds_read_b128 v[174:177], v141
	ds_read_b128 v[178:181], v141 offset:1024
	ds_read_b128 v[182:185], v141 offset:2048
	ds_read_b128 v[186:189], v141 offset:3072
	ds_read_b128 v[194:197], v141 offset:4096
	ds_read_b128 v[198:201], v141 offset:5120
	ds_read_b128 v[202:205], v141 offset:6144
	ds_read_b128 v[212:215], v141 offset:7168
	global_load_lds_dwordx4 v134, s[28:29]
	s_add_i32 m0, s68, 0xe000
	s_nop 0
	global_load_lds_dwordx4 v136, s[28:29]
	s_waitcnt vmcnt(8)
	s_waitcnt lgkmcnt(0)
	s_barrier
	s_setprio 1
	v_mfma_f32_16x16x32_bf16 v[124:127], v[142:145], v[174:177], v[124:127]
	v_mfma_f32_16x16x32_bf16 v[120:123], v[150:153], v[174:177], v[120:123]
	v_mfma_f32_16x16x32_bf16 v[108:111], v[142:145], v[182:185], v[108:111]
	v_mfma_f32_16x16x32_bf16 v[104:107], v[150:153], v[182:185], v[104:107]
	v_mfma_f32_16x16x32_bf16 v[92:95], v[142:145], v[194:197], v[92:95]
	v_mfma_f32_16x16x32_bf16 v[88:91], v[150:153], v[194:197], v[88:91]
	v_mfma_f32_16x16x32_bf16 v[76:79], v[142:145], v[202:205], v[76:79]
	v_mfma_f32_16x16x32_bf16 v[72:75], v[150:153], v[202:205], v[72:75]
	v_mfma_f32_16x16x32_bf16 v[124:127], v[146:149], v[178:181], v[124:127]
	v_mfma_f32_16x16x32_bf16 v[120:123], v[154:157], v[178:181], v[120:123]
	v_mfma_f32_16x16x32_bf16 v[108:111], v[146:149], v[186:189], v[108:111]
	v_mfma_f32_16x16x32_bf16 v[104:107], v[154:157], v[186:189], v[104:107]
	v_mfma_f32_16x16x32_bf16 v[92:95], v[146:149], v[198:201], v[92:95]
	v_mfma_f32_16x16x32_bf16 v[88:91], v[154:157], v[198:201], v[88:91]
	v_mfma_f32_16x16x32_bf16 v[76:79], v[146:149], v[212:215], v[76:79]
	v_mfma_f32_16x16x32_bf16 v[72:75], v[154:157], v[212:215], v[72:75]
	v_mfma_f32_16x16x32_bf16 v[116:119], v[158:161], v[174:177], v[116:119]
	v_mfma_f32_16x16x32_bf16 v[112:115], v[166:169], v[174:177], v[112:115]
	v_mfma_f32_16x16x32_bf16 v[100:103], v[158:161], v[182:185], v[100:103]
	v_mfma_f32_16x16x32_bf16 v[96:99], v[166:169], v[182:185], v[96:99]
	v_mfma_f32_16x16x32_bf16 v[84:87], v[158:161], v[194:197], v[84:87]
	v_mfma_f32_16x16x32_bf16 v[80:83], v[166:169], v[194:197], v[80:83]
	v_mfma_f32_16x16x32_bf16 v[68:71], v[158:161], v[202:205], v[68:71]
	v_mfma_f32_16x16x32_bf16 v[64:67], v[166:169], v[202:205], v[64:67]
	v_mfma_f32_16x16x32_bf16 v[116:119], v[162:165], v[178:181], v[116:119]
	v_mfma_f32_16x16x32_bf16 v[112:115], v[170:173], v[178:181], v[112:115]
	v_mfma_f32_16x16x32_bf16 v[100:103], v[162:165], v[186:189], v[100:103]
	v_mfma_f32_16x16x32_bf16 v[96:99], v[170:173], v[186:189], v[96:99]
	v_mfma_f32_16x16x32_bf16 v[84:87], v[162:165], v[198:201], v[84:87]
	v_mfma_f32_16x16x32_bf16 v[80:83], v[170:173], v[198:201], v[80:83]
	v_mfma_f32_16x16x32_bf16 v[68:71], v[162:165], v[212:215], v[68:71]
	v_mfma_f32_16x16x32_bf16 v[64:67], v[170:173], v[212:215], v[64:67]
	s_setprio 0
	s_barrier
	s_add_i32 s36, s36, s70
	s_mov_b64 vcc, s[12:13]
	s_mov_b32 m0, s36
	ds_read_b128 v[174:177], v141 offset:16384
	ds_read_b128 v[178:181], v141 offset:17408
	ds_read_b128 v[182:185], v141 offset:18432
	ds_read_b128 v[186:189], v141 offset:19456
	ds_read_b128 v[194:197], v141 offset:20480
	ds_read_b128 v[198:201], v141 offset:21504
	ds_read_b128 v[202:205], v141 offset:22528
	ds_read_b128 v[212:215], v141 offset:23552
	global_load_lds_dwordx4 v192, s[12:13]
	s_add_i32 m0, s36, 0x2000
	s_add_i32 s20, s20, s70
	global_load_lds_dwordx4 v128, s[12:13]
	s_add_u32 s12, s12, s58
	s_addc_u32 s13, s13, 0
	s_mov_b32 m0, s20
	s_nop 0
	global_load_lds_dwordx4 v192, s[12:13]
	s_add_i32 m0, s20, 0x2000
	s_nop 0
	global_load_lds_dwordx4 v128, s[12:13]
	s_mov_b32 m0, s68
	s_nop 0
	global_load_lds_dwordx4 v132, s[56:57]
	s_mov_b32 m0, s75
	s_nop 0
	global_load_lds_dwordx4 v130, s[56:57]
	s_waitcnt vmcnt(8)
	s_waitcnt lgkmcnt(0)
	s_barrier
	s_setprio 1
	v_mfma_f32_16x16x32_bf16 v[60:63], v[142:145], v[174:177], v[60:63]
	v_mfma_f32_16x16x32_bf16 v[56:59], v[150:153], v[174:177], v[56:59]
	v_mfma_f32_16x16x32_bf16 v[44:47], v[142:145], v[182:185], v[44:47]
	v_mfma_f32_16x16x32_bf16 v[40:43], v[150:153], v[182:185], v[40:43]
	v_mfma_f32_16x16x32_bf16 v[28:31], v[142:145], v[194:197], v[28:31]
	v_mfma_f32_16x16x32_bf16 v[24:27], v[150:153], v[194:197], v[24:27]
	v_mfma_f32_16x16x32_bf16 v[12:15], v[142:145], v[202:205], v[12:15]
	v_mfma_f32_16x16x32_bf16 v[8:11], v[150:153], v[202:205], v[8:11]
	v_mfma_f32_16x16x32_bf16 v[60:63], v[146:149], v[178:181], v[60:63]
	v_mfma_f32_16x16x32_bf16 v[56:59], v[154:157], v[178:181], v[56:59]
	v_mfma_f32_16x16x32_bf16 v[44:47], v[146:149], v[186:189], v[44:47]
	v_mfma_f32_16x16x32_bf16 v[40:43], v[154:157], v[186:189], v[40:43]
	v_mfma_f32_16x16x32_bf16 v[28:31], v[146:149], v[198:201], v[28:31]
	v_mfma_f32_16x16x32_bf16 v[24:27], v[154:157], v[198:201], v[24:27]
	v_mfma_f32_16x16x32_bf16 v[12:15], v[146:149], v[212:215], v[12:15]
	v_mfma_f32_16x16x32_bf16 v[8:11], v[154:157], v[212:215], v[8:11]
	v_mfma_f32_16x16x32_bf16 v[52:55], v[158:161], v[174:177], v[52:55]
	v_mfma_f32_16x16x32_bf16 v[48:51], v[166:169], v[174:177], v[48:51]
	v_mfma_f32_16x16x32_bf16 v[36:39], v[158:161], v[182:185], v[36:39]
	v_mfma_f32_16x16x32_bf16 v[32:35], v[166:169], v[182:185], v[32:35]
	v_mfma_f32_16x16x32_bf16 v[20:23], v[158:161], v[194:197], v[20:23]
	v_mfma_f32_16x16x32_bf16 v[16:19], v[166:169], v[194:197], v[16:19]
	v_mfma_f32_16x16x32_bf16 v[4:7], v[158:161], v[202:205], v[4:7]
	v_mfma_f32_16x16x32_bf16 v[0:3], v[166:169], v[202:205], v[0:3]
	v_mfma_f32_16x16x32_bf16 v[52:55], v[162:165], v[178:181], v[52:55]
	v_mfma_f32_16x16x32_bf16 v[48:51], v[170:173], v[178:181], v[48:51]
	v_mfma_f32_16x16x32_bf16 v[36:39], v[162:165], v[186:189], v[36:39]
	v_mfma_f32_16x16x32_bf16 v[32:35], v[170:173], v[186:189], v[32:35]
	v_mfma_f32_16x16x32_bf16 v[20:23], v[162:165], v[198:201], v[20:23]
	v_mfma_f32_16x16x32_bf16 v[16:19], v[170:173], v[198:201], v[16:19]
	v_mfma_f32_16x16x32_bf16 v[4:7], v[162:165], v[212:215], v[4:7]
	v_mfma_f32_16x16x32_bf16 v[0:3], v[170:173], v[212:215], v[0:3]
	s_setprio 0
	s_barrier
	s_add_i32 s20, 0, 0x18000
	s_add_i32 s36, 0, 0x1c000
	v_add_u32_e32 v154, s20, v139
	v_add_u32_e32 v170, s36, v139
	ds_read_b128 v[142:145], v154
	ds_read_b128 v[146:149], v154 offset:1024
	ds_read_b128 v[150:153], v154 offset:2048
	ds_read_b128 v[154:157], v154 offset:3072
	ds_read_b128 v[158:161], v170
	ds_read_b128 v[162:165], v170 offset:1024
	ds_read_b128 v[166:169], v170 offset:2048
	ds_read_b128 v[170:173], v170 offset:3072
	s_add_u32 s12, s56, s34
	s_addc_u32 s13, s57, 0
	s_mov_b32 m0, s76
	ds_read_b128 v[174:177], v141 offset:32768
	ds_read_b128 v[178:181], v141 offset:33792
	ds_read_b128 v[182:185], v141 offset:34816
	ds_read_b128 v[186:189], v141 offset:35840
	ds_read_b128 v[194:197], v141 offset:36864
	ds_read_b128 v[198:201], v141 offset:37888
	ds_read_b128 v[202:205], v141 offset:38912
	ds_read_b128 v[212:215], v141 offset:39936
	global_load_lds_dwordx4 v132, s[12:13]
	s_mov_b32 m0, s77
	s_nop 0
	global_load_lds_dwordx4 v130, s[12:13]
	s_waitcnt vmcnt(8)
	s_waitcnt lgkmcnt(0)
	s_barrier
	s_setprio 1
	v_mfma_f32_16x16x32_bf16 v[124:127], v[142:145], v[174:177], v[124:127]
	v_mfma_f32_16x16x32_bf16 v[120:123], v[150:153], v[174:177], v[120:123]
	v_mfma_f32_16x16x32_bf16 v[108:111], v[142:145], v[182:185], v[108:111]
	v_mfma_f32_16x16x32_bf16 v[104:107], v[150:153], v[182:185], v[104:107]
	v_mfma_f32_16x16x32_bf16 v[92:95], v[142:145], v[194:197], v[92:95]
	v_mfma_f32_16x16x32_bf16 v[88:91], v[150:153], v[194:197], v[88:91]
	v_mfma_f32_16x16x32_bf16 v[76:79], v[142:145], v[202:205], v[76:79]
	v_mfma_f32_16x16x32_bf16 v[72:75], v[150:153], v[202:205], v[72:75]
	v_mfma_f32_16x16x32_bf16 v[124:127], v[146:149], v[178:181], v[124:127]
	v_mfma_f32_16x16x32_bf16 v[120:123], v[154:157], v[178:181], v[120:123]
	v_mfma_f32_16x16x32_bf16 v[108:111], v[146:149], v[186:189], v[108:111]
	v_mfma_f32_16x16x32_bf16 v[104:107], v[154:157], v[186:189], v[104:107]
	v_mfma_f32_16x16x32_bf16 v[92:95], v[146:149], v[198:201], v[92:95]
	v_mfma_f32_16x16x32_bf16 v[88:91], v[154:157], v[198:201], v[88:91]
	v_mfma_f32_16x16x32_bf16 v[76:79], v[146:149], v[212:215], v[76:79]
	v_mfma_f32_16x16x32_bf16 v[72:75], v[154:157], v[212:215], v[72:75]
	v_mfma_f32_16x16x32_bf16 v[116:119], v[158:161], v[174:177], v[116:119]
	v_mfma_f32_16x16x32_bf16 v[112:115], v[166:169], v[174:177], v[112:115]
	v_mfma_f32_16x16x32_bf16 v[100:103], v[158:161], v[182:185], v[100:103]
	v_mfma_f32_16x16x32_bf16 v[96:99], v[166:169], v[182:185], v[96:99]
	v_mfma_f32_16x16x32_bf16 v[84:87], v[158:161], v[194:197], v[84:87]
	v_mfma_f32_16x16x32_bf16 v[80:83], v[166:169], v[194:197], v[80:83]
	v_mfma_f32_16x16x32_bf16 v[68:71], v[158:161], v[202:205], v[68:71]
	v_mfma_f32_16x16x32_bf16 v[64:67], v[166:169], v[202:205], v[64:67]
	v_mfma_f32_16x16x32_bf16 v[116:119], v[162:165], v[178:181], v[116:119]
	v_mfma_f32_16x16x32_bf16 v[112:115], v[170:173], v[178:181], v[112:115]
	v_mfma_f32_16x16x32_bf16 v[100:103], v[162:165], v[186:189], v[100:103]
	v_mfma_f32_16x16x32_bf16 v[96:99], v[170:173], v[186:189], v[96:99]
	v_mfma_f32_16x16x32_bf16 v[84:87], v[162:165], v[198:201], v[84:87]
	v_mfma_f32_16x16x32_bf16 v[80:83], v[170:173], v[198:201], v[80:83]
	v_mfma_f32_16x16x32_bf16 v[68:71], v[162:165], v[212:215], v[68:71]
	v_mfma_f32_16x16x32_bf16 v[64:67], v[170:173], v[212:215], v[64:67]
	s_setprio 0
	s_barrier
	s_add_i32 m0, s20, s70
	s_add_u32 s12, vcc_lo, 0x80
	s_addc_u32 s13, vcc_hi, 0
	ds_read_b128 v[174:177], v141 offset:49152
	ds_read_b128 v[178:181], v141 offset:50176
	ds_read_b128 v[182:185], v141 offset:51200
	ds_read_b128 v[186:189], v141 offset:52224
	ds_read_b128 v[194:197], v141 offset:53248
	ds_read_b128 v[198:201], v141 offset:54272
	ds_read_b128 v[202:205], v141 offset:55296
	ds_read_b128 v[212:215], v141 offset:56320
	global_load_lds_dwordx4 v192, s[12:13]
	s_add_i32 m0, m0, 0x2000
	s_nop 0
	global_load_lds_dwordx4 v128, s[12:13]
	s_add_u32 s12, s12, s58
	s_addc_u32 s13, s13, 0
	s_add_i32 m0, s36, s70
	s_nop 0
	global_load_lds_dwordx4 v192, s[12:13]
	s_add_i32 m0, m0, 0x2000
	s_nop 0
	global_load_lds_dwordx4 v128, s[12:13]
	s_add_u32 s12, s56, 0x80
	s_addc_u32 s13, s57, 0
	s_mov_b32 m0, s78
	s_nop 0
	global_load_lds_dwordx4 v132, s[12:13]
	s_mov_b32 m0, s79
	s_nop 0
	global_load_lds_dwordx4 v130, s[12:13]
	s_waitcnt vmcnt(8)
	s_waitcnt lgkmcnt(0)
	s_barrier
	s_setprio 1
	v_mfma_f32_16x16x32_bf16 v[60:63], v[142:145], v[174:177], v[60:63]
	v_mfma_f32_16x16x32_bf16 v[56:59], v[150:153], v[174:177], v[56:59]
	v_mfma_f32_16x16x32_bf16 v[44:47], v[142:145], v[182:185], v[44:47]
	v_mfma_f32_16x16x32_bf16 v[40:43], v[150:153], v[182:185], v[40:43]
	v_mfma_f32_16x16x32_bf16 v[28:31], v[142:145], v[194:197], v[28:31]
	v_mfma_f32_16x16x32_bf16 v[24:27], v[150:153], v[194:197], v[24:27]
	v_mfma_f32_16x16x32_bf16 v[12:15], v[142:145], v[202:205], v[12:15]
	v_mfma_f32_16x16x32_bf16 v[8:11], v[150:153], v[202:205], v[8:11]
	v_mfma_f32_16x16x32_bf16 v[60:63], v[146:149], v[178:181], v[60:63]
	v_mfma_f32_16x16x32_bf16 v[56:59], v[154:157], v[178:181], v[56:59]
	v_mfma_f32_16x16x32_bf16 v[44:47], v[146:149], v[186:189], v[44:47]
	v_mfma_f32_16x16x32_bf16 v[40:43], v[154:157], v[186:189], v[40:43]
	v_mfma_f32_16x16x32_bf16 v[28:31], v[146:149], v[198:201], v[28:31]
	v_mfma_f32_16x16x32_bf16 v[24:27], v[154:157], v[198:201], v[24:27]
	v_mfma_f32_16x16x32_bf16 v[12:15], v[146:149], v[212:215], v[12:15]
	v_mfma_f32_16x16x32_bf16 v[8:11], v[154:157], v[212:215], v[8:11]
	v_mfma_f32_16x16x32_bf16 v[52:55], v[158:161], v[174:177], v[52:55]
	v_mfma_f32_16x16x32_bf16 v[48:51], v[166:169], v[174:177], v[48:51]
	v_mfma_f32_16x16x32_bf16 v[36:39], v[158:161], v[182:185], v[36:39]
	v_mfma_f32_16x16x32_bf16 v[32:35], v[166:169], v[182:185], v[32:35]
	v_mfma_f32_16x16x32_bf16 v[20:23], v[158:161], v[194:197], v[20:23]
	v_mfma_f32_16x16x32_bf16 v[16:19], v[166:169], v[194:197], v[16:19]
	v_mfma_f32_16x16x32_bf16 v[4:7], v[158:161], v[202:205], v[4:7]
	v_mfma_f32_16x16x32_bf16 v[0:3], v[166:169], v[202:205], v[0:3]
	v_mfma_f32_16x16x32_bf16 v[52:55], v[162:165], v[178:181], v[52:55]
	v_mfma_f32_16x16x32_bf16 v[48:51], v[170:173], v[178:181], v[48:51]
	v_mfma_f32_16x16x32_bf16 v[36:39], v[162:165], v[186:189], v[36:39]
	v_mfma_f32_16x16x32_bf16 v[32:35], v[170:173], v[186:189], v[32:35]
	v_mfma_f32_16x16x32_bf16 v[20:23], v[162:165], v[198:201], v[20:23]
	v_mfma_f32_16x16x32_bf16 v[16:19], v[170:173], v[198:201], v[16:19]
	v_mfma_f32_16x16x32_bf16 v[4:7], v[162:165], v[212:215], v[4:7]
	v_mfma_f32_16x16x32_bf16 v[0:3], v[170:173], v[212:215], v[0:3]
	s_setprio 0
	s_add_u32 s28, s28, 0x100
	s_addc_u32 s29, s29, 0
	s_add_u32 s18, s18, 0x100
	s_addc_u32 s19, s19, 0
	s_cmp_ge_u32 s21, s80
	s_mov_b32 s20, s21
	s_barrier
	s_cbranch_scc0 .LBB0_188
	s_and_b64 vcc, exec, s[48:49]
	s_cbranch_vccz .LBB0_191
